# EpiWin non-rotary tiles: per-element activation branching replaced by three straight-line variants (plain/silu/gelu), packed f32 math
# speedup vs baseline: 1.0015x; 1.0015x over previous
; #define LAS __attribute__((address_space(3)))
; __device__ __forceinline__ void rows_rstd(LAS unsigned char* sl, int rl0, int fq, float (&rs)[8]) {
;     f32x4 v[8];
; #pragma unroll
;     for (int i = 0; i < 8; ++i) v[i] = *(const LAS f32x4*)(sl + (rl0 + (i >> 2) * 128 + (i & 3) * 16) * 64 + fq * 16);
; #pragma unroll
;     for (int i = 0; i < 8; ++i) { float s = (v[i].x + v[i].y) + (v[i].z + v[i].w); s += __shfl_xor(s, 16); s += __shfl_xor(s, 32); rs[i] = rsqrtf(s * (1.0f / DM) + EPS); }
; }
;     __device__ __forceinline__ void operator()(const f32x4 (&acc)[2][2][4][2], const pg8::Unit& u, int wr, int wc, int fr, int fq) const {
;         const int row0 = u.pm * 256 + wr * 64 + fr, pn = u.pn;
;         float rs[8]; rows_rstd(sl, wr * 64 + fr, fq, rs);
;         if (pn >= 1 && pn <= 4) {
;             const float qs = (pn <= 2) ? 0.08838834764831845f : 1.0f;
.LBB0_249:
	s_add_i32 s4, s45, -1
	s_cmp_gt_u32 s4, 3
	s_cbranch_scc1 .Lwin_act
	v_and_b32_e32 v171, 64, v175
	v_xor_b32_e32 v144, 16, v175
	v_add_u32_e32 v171, 64, v171
	v_cmp_lt_i32_e32 vcc, v144, v171
	v_xor_b32_e32 v172, 32, v175
	ds_read_b128 v[180:183], v200
	ds_read_b128 v[202:205], v200 offset:1024
	ds_read_b128 v[208:211], v200 offset:2048
	ds_read_b128 v[212:215], v200 offset:3072
	ds_read_b128 v[140:143], v200 offset:8192
	ds_read_b128 v[136:139], v200 offset:9216
	ds_read_b128 v[132:135], v200 offset:10240
	ds_read_b128 v[128:131], v200 offset:11264
	v_cndmask_b32_e32 v144, v175, v144, vcc
	v_cmp_lt_i32_e32 vcc, v172, v171
	s_waitcnt lgkmcnt(0)
	v_mov_b32_e32 v173, v182
	v_lshlrev_b32_e32 v144, 2, v144
	v_cndmask_b32_e32 v171, v175, v172, vcc
	v_mov_b32_e32 v172, v181
	v_mov_b32_e32 v181, v183
	v_pk_add_f32 v[172:173], v[172:173], v[180:181]
	v_mov_b32_e32 v180, v203
	v_mov_b32_e32 v181, v204
	v_mov_b32_e32 v203, v205
	v_pk_add_f32 v[180:181], v[180:181], v[202:203]
	v_mov_b32_e32 v183, v172
	v_mov_b32_e32 v182, v180
	v_mov_b32_e32 v172, v181
	v_pk_add_f32 v[172:173], v[182:183], v[172:173]
	ds_bpermute_b32 v181, v144, v173
	ds_bpermute_b32 v180, v144, v172
	v_lshlrev_b32_e32 v186, 2, v171
	s_mov_b32 s0, 0x358637bd
	v_mov_b32_e32 v182, v213
	v_mov_b32_e32 v183, v214
	s_waitcnt lgkmcnt(0)
	v_pk_add_f32 v[172:173], v[172:173], v[180:181]
	ds_bpermute_b32 v181, v186, v173
	ds_bpermute_b32 v180, v186, v172
	v_mov_b32_e32 v213, v215
	v_pk_add_f32 v[182:183], v[182:183], v[212:213]
	s_add_i32 s4, s45, -1
	v_mov_b32_e32 v184, v182
	s_waitcnt lgkmcnt(0)
	v_pk_add_f32 v[180:181], v[172:173], v[180:181]
	v_mov_b64_e32 v[172:173], s[0:1]
	s_mov_b32 s0, 0x3a800000
	v_pk_fma_f32 v[180:181], v[180:181], s[0:1], v[172:173] op_sel_hi:[1,0,0]
	v_add_u32_e32 v201, s47, v159
	v_mul_f32_e32 v171, 0x4b800000, v181
	v_cmp_gt_f32_e64 s[38:39], s33, v181
	v_cmp_gt_f32_e32 vcc, s33, v180
	s_cmp_gt_u32 s4, 3
	v_cndmask_b32_e64 v171, v181, v171, s[38:39]
	v_rsq_f32_e32 v171, v171
	s_nop 0
	v_mul_f32_e32 v181, 0x45800000, v171
	v_cndmask_b32_e64 v171, v171, v181, s[38:39]
	v_mul_f32_e32 v181, 0x4b800000, v180
	v_cndmask_b32_e32 v180, v180, v181, vcc
	v_rsq_f32_e32 v180, v180
	s_nop 0
	v_mul_f32_e32 v181, 0x45800000, v180
	v_cndmask_b32_e32 v206, v180, v181, vcc
	v_mov_b32_e32 v180, v209
	v_mov_b32_e32 v181, v210
	v_mov_b32_e32 v209, v211
	v_pk_add_f32 v[180:181], v[180:181], v[208:209]
	s_nop 0
	v_mov_b32_e32 v185, v180
	v_mov_b32_e32 v180, v183
	v_pk_add_f32 v[180:181], v[184:185], v[180:181]
	ds_bpermute_b32 v183, v144, v181
	ds_bpermute_b32 v182, v144, v180
	s_waitcnt lgkmcnt(0)
	v_pk_add_f32 v[180:181], v[180:181], v[182:183]
	ds_bpermute_b32 v183, v186, v181
	ds_bpermute_b32 v182, v186, v180
	s_waitcnt lgkmcnt(0)
	v_pk_add_f32 v[180:181], v[180:181], v[182:183]
	s_nop 0
	v_pk_fma_f32 v[180:181], v[180:181], s[0:1], v[172:173] op_sel_hi:[1,0,0]
	s_nop 0
	v_mul_f32_e32 v182, 0x4b800000, v181
	v_cmp_gt_f32_e64 s[38:39], s33, v181
	v_cmp_gt_f32_e32 vcc, s33, v180
	s_nop 0
	v_cndmask_b32_e64 v181, v181, v182, s[38:39]
	v_rsq_f32_e32 v181, v181
	s_nop 0
	v_mul_f32_e32 v182, 0x45800000, v181
	v_cndmask_b32_e64 v205, v181, v182, s[38:39]
	v_mul_f32_e32 v181, 0x4b800000, v180
	v_cndmask_b32_e32 v180, v180, v181, vcc
	v_rsq_f32_e32 v180, v180
	s_nop 0
	v_mul_f32_e32 v181, 0x45800000, v180
	v_cndmask_b32_e32 v204, v180, v181, vcc
	v_mov_b32_e32 v180, v141
	v_mov_b32_e32 v181, v142
	v_mov_b32_e32 v141, v143
	v_mov_b32_e32 v142, v137
	v_mov_b32_e32 v143, v138
	v_mov_b32_e32 v137, v139
	v_pk_add_f32 v[140:141], v[180:181], v[140:141]
	v_pk_add_f32 v[136:137], v[142:143], v[136:137]
	v_mov_b32_e32 v139, v140
	v_mov_b32_e32 v138, v136
	v_mov_b32_e32 v140, v137
	v_pk_add_f32 v[136:137], v[138:139], v[140:141]
	ds_bpermute_b32 v139, v144, v137
	ds_bpermute_b32 v138, v144, v136
	s_waitcnt lgkmcnt(0)
	v_pk_add_f32 v[136:137], v[136:137], v[138:139]
	ds_bpermute_b32 v139, v186, v137
	ds_bpermute_b32 v138, v186, v136
	s_waitcnt lgkmcnt(0)
	v_pk_add_f32 v[136:137], v[136:137], v[138:139]
	s_nop 0
	v_pk_fma_f32 v[136:137], v[136:137], s[0:1], v[172:173] op_sel_hi:[1,0,0]
	s_nop 0
	v_mul_f32_e32 v138, 0x4b800000, v137
	v_cmp_gt_f32_e64 s[38:39], s33, v137
	v_cmp_gt_f32_e32 vcc, s33, v136
	s_nop 0
	v_cndmask_b32_e64 v137, v137, v138, s[38:39]
	v_rsq_f32_e32 v137, v137
	s_nop 0
	v_mul_f32_e32 v138, 0x45800000, v137
	v_cndmask_b32_e64 v203, v137, v138, s[38:39]
	v_mul_f32_e32 v137, 0x4b800000, v136
	v_cndmask_b32_e32 v136, v136, v137, vcc
	v_rsq_f32_e32 v136, v136
	s_nop 0
	v_mul_f32_e32 v137, 0x45800000, v136
	v_cndmask_b32_e32 v202, v136, v137, vcc
	v_mov_b32_e32 v136, v133
	v_mov_b32_e32 v137, v134
	v_mov_b32_e32 v133, v135
	v_mov_b32_e32 v134, v129
	v_mov_b32_e32 v135, v130
	v_mov_b32_e32 v129, v131
	v_pk_add_f32 v[132:133], v[136:137], v[132:133]
	v_pk_add_f32 v[128:129], v[134:135], v[128:129]
	v_mov_b32_e32 v131, v132
	v_mov_b32_e32 v130, v128
	v_mov_b32_e32 v132, v129
	v_pk_add_f32 v[128:129], v[130:131], v[132:133]
	ds_bpermute_b32 v131, v144, v129
	ds_bpermute_b32 v130, v144, v128
	s_waitcnt lgkmcnt(0)
	v_pk_add_f32 v[128:129], v[128:129], v[130:131]
	ds_bpermute_b32 v131, v186, v129
	ds_bpermute_b32 v130, v186, v128
	s_waitcnt lgkmcnt(0)
	v_pk_add_f32 v[128:129], v[128:129], v[130:131]
	s_nop 0
	v_pk_fma_f32 v[128:129], v[128:129], s[0:1], v[172:173] op_sel_hi:[1,0,0]
	s_mov_b64 s[0:1], -1
	v_mul_f32_e32 v130, 0x4b800000, v129
	v_cmp_gt_f32_e64 s[38:39], s33, v129
	v_cmp_gt_f32_e32 vcc, s33, v128
	s_nop 0
	v_cndmask_b32_e64 v129, v129, v130, s[38:39]
	v_rsq_f32_e32 v129, v129
	s_nop 0
	v_mul_f32_e32 v130, 0x45800000, v129
	v_cndmask_b32_e64 v173, v129, v130, s[38:39]
	v_mul_f32_e32 v129, 0x4b800000, v128
	v_cndmask_b32_e32 v128, v128, v129, vcc
	v_rsq_f32_e32 v128, v128
	s_nop 0
	v_mul_f32_e32 v129, 0x45800000, v128
	v_cndmask_b32_e32 v172, v128, v129, vcc
	s_branch .LBB0_266

; #define LAS __attribute__((address_space(3)))
; __device__ __forceinline__ unsigned pk2(float lo, float hi) { return pg8::cvt_pk_bf16(lo, hi); }
; __device__ __forceinline__ float siluf_(float x) { return x * sigmoidf_(x); }
; __device__ __forceinline__ float geluf_(float x) { const float z = 1.5957691216057308f * (x + 0.044715f * x * x * x); return x * sigmoidf_(z); }
; __device__ __forceinline__ void rows_rstd(LAS unsigned char* sl, int rl0, int fq, float (&rs)[8]) {
;     f32x4 v[8];
; #pragma unroll
;     for (int i = 0; i < 8; ++i) v[i] = *(const LAS f32x4*)(sl + (rl0 + (i >> 2) * 128 + (i & 3) * 16) * 64 + fq * 16);
; #pragma unroll
;     for (int i = 0; i < 8; ++i) { float s = (v[i].x + v[i].y) + (v[i].z + v[i].w); s += __shfl_xor(s, 16); s += __shfl_xor(s, 32); rs[i] = rsqrtf(s * (1.0f / DM) + EPS); }
; }
;     __device__ __forceinline__ void operator()(const f32x4 (&acc)[2][2][4][2], const pg8::Unit& u, int wr, int wc, int fr, int fq) const {
;     ...
;             const int act = (pn == 7 || pn == 8) ? 1 : (pn == 10 ? 2 : 0);
; #pragma unroll
;             for (int ai = 0; ai < 2; ++ai)
; #pragma unroll
;                 for (int m = 0; m < 4; ++m) {
;                     const int row = row0 + ai * 128 + m * 16; const float r = rs[ai * 4 + m];
; #pragma unroll
;                     for (int bj = 0; bj < 2; ++bj) {
;                         float v[8];
; #pragma unroll
;                         for (int n = 0; n < 2; ++n)
; #pragma unroll
;                             for (int j = 0; j < 4; ++j) { float t = acc[ai][bj][m][n][j] * r; if (act == 1) t = siluf_(t); else if (act == 2) t = geluf_(t); v[n * 4 + j] = t; }
;                         u32x4 w; w.x = pk2(v[0], v[1]); w.y = pk2(v[2], v[3]); w.z = pk2(v[4], v[5]); w.w = pk2(v[6], v[7]);
;                         *(u32x4*)(Z + (size_t)row * IW + pn * 256 + bj * 128 + wc * 32 + 8 * fq) = w;
;                     }
.Lwin_act:
	v_xor_b32_e32 v130, 16, v175
	v_xor_b32_e32 v131, 32, v175
	ds_read_b128 v[202:205], v200
	ds_read_b128 v[206:209], v200 offset:1024
	ds_read_b128 v[210:213], v200 offset:2048
	ds_read_b128 v[214:217], v200 offset:3072
	ds_read_b128 v[218:221], v200 offset:8192
	ds_read_b128 v[222:225], v200 offset:9216
	ds_read_b128 v[226:229], v200 offset:10240
	ds_read_b128 v[230:233], v200 offset:11264
	v_lshlrev_b32_e32 v130, 2, v130
	v_lshlrev_b32_e32 v131, 2, v131
	v_mov_b32_e32 v128, 1.0
	v_mov_b32_e32 v129, 1.0
	v_mov_b32_e32 v132, 0xbfb8aa3b
	v_mov_b32_e32 v134, 0x3d372713
	v_mov_b32_e32 v136, 0x3fcc422a
	v_mov_b32_e32 v138, 0x3a800000
	v_add_u32_e32 v139, s47, v159
	v_mul_u32_u24_e32 v139, 0x1600, v139
	v_bfe_u32 v140, v174, 6, 2
	v_bfe_u32 v141, v174, 4, 2
	v_lshlrev_b32_e32 v140, 6, v140
	v_lshl_add_u32 v140, v141, 4, v140
	s_lshl_b32 s4, s45, 9
	v_add3_u32 v139, v139, v140, s4
	s_waitcnt lgkmcnt(0)
	v_add_f32_e32 v234, v202, v203
	v_add_f32_e32 v235, v206, v207
	v_add_f32_e32 v236, v210, v211
	v_add_f32_e32 v237, v214, v215
	v_add_f32_e32 v238, v218, v219
	v_add_f32_e32 v239, v222, v223
	v_add_f32_e32 v240, v226, v227
	v_add_f32_e32 v241, v230, v231
	v_add_f32_e32 v242, v204, v205
	v_add_f32_e32 v243, v208, v209
	v_add_f32_e32 v244, v212, v213
	v_add_f32_e32 v245, v216, v217
	v_add_f32_e32 v246, v220, v221
	v_add_f32_e32 v247, v224, v225
	v_add_f32_e32 v248, v228, v229
	v_add_f32_e32 v249, v232, v233
	v_add_f32_e32 v234, v234, v242
	v_add_f32_e32 v235, v235, v243
	v_add_f32_e32 v236, v236, v244
	v_add_f32_e32 v237, v237, v245
	v_add_f32_e32 v238, v238, v246
	v_add_f32_e32 v239, v239, v247
	v_add_f32_e32 v240, v240, v248
	v_add_f32_e32 v241, v241, v249
	ds_bpermute_b32 v242, v130, v234
	ds_bpermute_b32 v243, v130, v235
	ds_bpermute_b32 v244, v130, v236
	ds_bpermute_b32 v245, v130, v237
	ds_bpermute_b32 v246, v130, v238
	ds_bpermute_b32 v247, v130, v239
	ds_bpermute_b32 v248, v130, v240
	ds_bpermute_b32 v249, v130, v241
	s_waitcnt lgkmcnt(0)
	v_add_f32_e32 v234, v234, v242
	v_add_f32_e32 v235, v235, v243
	v_add_f32_e32 v236, v236, v244
	v_add_f32_e32 v237, v237, v245
	v_add_f32_e32 v238, v238, v246
	v_add_f32_e32 v239, v239, v247
	v_add_f32_e32 v240, v240, v248
	v_add_f32_e32 v241, v241, v249
	ds_bpermute_b32 v242, v131, v234
	ds_bpermute_b32 v243, v131, v235
	ds_bpermute_b32 v244, v131, v236
	ds_bpermute_b32 v245, v131, v237
	ds_bpermute_b32 v246, v131, v238
	ds_bpermute_b32 v247, v131, v239
	ds_bpermute_b32 v248, v131, v240
	ds_bpermute_b32 v249, v131, v241
	s_waitcnt lgkmcnt(0)
	v_add_f32_e32 v234, v234, v242
	v_add_f32_e32 v235, v235, v243
	v_add_f32_e32 v236, v236, v244
	v_add_f32_e32 v237, v237, v245
	v_add_f32_e32 v238, v238, v246
	v_add_f32_e32 v239, v239, v247
	v_add_f32_e32 v240, v240, v248
	v_add_f32_e32 v241, v241, v249
	v_fmaak_f32 v234, v138, v234, 0x358637bd
	v_fmaak_f32 v235, v138, v235, 0x358637bd
	v_fmaak_f32 v236, v138, v236, 0x358637bd
	v_fmaak_f32 v237, v138, v237, 0x358637bd
	v_fmaak_f32 v238, v138, v238, 0x358637bd
	v_fmaak_f32 v239, v138, v239, 0x358637bd
	v_fmaak_f32 v240, v138, v240, 0x358637bd
	v_fmaak_f32 v241, v138, v241, 0x358637bd
	v_rsq_f32_e32 v202, v234
	v_rsq_f32_e32 v204, v235
	v_rsq_f32_e32 v206, v236
	v_rsq_f32_e32 v208, v237
	v_rsq_f32_e32 v210, v238
	v_rsq_f32_e32 v212, v239
	v_rsq_f32_e32 v214, v240
	v_rsq_f32_e32 v216, v241
	s_cmp_eq_u32 s45, 10
	s_cbranch_scc1 .Lwin_act_gelu
	s_add_i32 s4, s45, -7
	s_cmp_lt_u32 s4, 2
	s_cbranch_scc1 .Lwin_act_silu
	v_pk_mul_f32 v[124:125], v[124:125], v[202:203] op_sel_hi:[1,0]
	v_pk_mul_f32 v[126:127], v[126:127], v[202:203] op_sel_hi:[1,0]
	v_pk_mul_f32 v[120:121], v[120:121], v[202:203] op_sel_hi:[1,0]
	v_pk_mul_f32 v[122:123], v[122:123], v[202:203] op_sel_hi:[1,0]
	v_pk_mul_f32 v[116:117], v[116:117], v[202:203] op_sel_hi:[1,0]
	v_pk_mul_f32 v[118:119], v[118:119], v[202:203] op_sel_hi:[1,0]
	v_pk_mul_f32 v[112:113], v[112:113], v[202:203] op_sel_hi:[1,0]
	v_pk_mul_f32 v[114:115], v[114:115], v[202:203] op_sel_hi:[1,0]
	v_cvt_pk_bf16_f32 v124, v124, v125
	v_cvt_pk_bf16_f32 v125, v126, v127
	v_cvt_pk_bf16_f32 v126, v120, v121
	v_cvt_pk_bf16_f32 v127, v122, v123
	v_cvt_pk_bf16_f32 v116, v116, v117
	v_cvt_pk_bf16_f32 v117, v118, v119
	v_cvt_pk_bf16_f32 v118, v112, v113
	v_cvt_pk_bf16_f32 v119, v114, v115
	v_mov_b32_e32 v140, v139
	global_store_dwordx4 v140, v[124:127], s[8:9]
	v_add_u32_e32 v141, 0x100, v139
	global_store_dwordx4 v141, v[116:119], s[8:9]
	v_pk_mul_f32 v[108:109], v[108:109], v[204:205] op_sel_hi:[1,0]
	v_pk_mul_f32 v[110:111], v[110:111], v[204:205] op_sel_hi:[1,0]
	v_pk_mul_f32 v[104:105], v[104:105], v[204:205] op_sel_hi:[1,0]
	v_pk_mul_f32 v[106:107], v[106:107], v[204:205] op_sel_hi:[1,0]
	v_pk_mul_f32 v[100:101], v[100:101], v[204:205] op_sel_hi:[1,0]
	v_pk_mul_f32 v[102:103], v[102:103], v[204:205] op_sel_hi:[1,0]
	v_pk_mul_f32 v[96:97], v[96:97], v[204:205] op_sel_hi:[1,0]
	v_pk_mul_f32 v[98:99], v[98:99], v[204:205] op_sel_hi:[1,0]
	v_cvt_pk_bf16_f32 v108, v108, v109
	v_cvt_pk_bf16_f32 v109, v110, v111
	v_cvt_pk_bf16_f32 v110, v104, v105
	v_cvt_pk_bf16_f32 v111, v106, v107
	v_cvt_pk_bf16_f32 v100, v100, v101
	v_cvt_pk_bf16_f32 v101, v102, v103
	v_cvt_pk_bf16_f32 v102, v96, v97
	v_cvt_pk_bf16_f32 v103, v98, v99
	v_add_u32_e32 v140, 0x16000, v139
	global_store_dwordx4 v140, v[108:111], s[8:9]
	v_add_u32_e32 v141, 0x16100, v139
	global_store_dwordx4 v141, v[100:103], s[8:9]
	v_pk_mul_f32 v[92:93], v[92:93], v[206:207] op_sel_hi:[1,0]
	v_pk_mul_f32 v[94:95], v[94:95], v[206:207] op_sel_hi:[1,0]
	v_pk_mul_f32 v[88:89], v[88:89], v[206:207] op_sel_hi:[1,0]
	v_pk_mul_f32 v[90:91], v[90:91], v[206:207] op_sel_hi:[1,0]
; __device__ __forceinline__ unsigned pk2(float lo, float hi) { return pg8::cvt_pk_bf16(lo, hi); }
; __device__ __forceinline__ float siluf_(float x) { return x * sigmoidf_(x); }
; __device__ __forceinline__ float geluf_(float x) { const float z = 1.5957691216057308f * (x + 0.044715f * x * x * x); return x * sigmoidf_(z); }
;     __device__ __forceinline__ void operator()(const f32x4 (&acc)[2][2][4][2], const pg8::Unit& u, int wr, int wc, int fr, int fq) const {
;     ...
;             for (int ai = 0; ai < 2; ++ai)
; #pragma unroll
;                 for (int m = 0; m < 4; ++m) {
;                     const int row = row0 + ai * 128 + m * 16; const float r = rs[ai * 4 + m];
; #pragma unroll
;                     for (int bj = 0; bj < 2; ++bj) {
;                         float v[8];
; #pragma unroll
;                         for (int n = 0; n < 2; ++n)
; #pragma unroll
;                             for (int j = 0; j < 4; ++j) { float t = acc[ai][bj][m][n][j] * r; if (act == 1) t = siluf_(t); else if (act == 2) t = geluf_(t); v[n * 4 + j] = t; }
;                         u32x4 w; w.x = pk2(v[0], v[1]); w.y = pk2(v[2], v[3]); w.z = pk2(v[4], v[5]); w.w = pk2(v[6], v[7]);
;                         *(u32x4*)(Z + (size_t)row * IW + pn * 256 + bj * 128 + wc * 32 + 8 * fq) = w;
;                     }
	v_pk_mul_f32 v[84:85], v[84:85], v[206:207] op_sel_hi:[1,0]
	v_pk_mul_f32 v[86:87], v[86:87], v[206:207] op_sel_hi:[1,0]
	v_pk_mul_f32 v[80:81], v[80:81], v[206:207] op_sel_hi:[1,0]
	v_pk_mul_f32 v[82:83], v[82:83], v[206:207] op_sel_hi:[1,0]
	v_cvt_pk_bf16_f32 v92, v92, v93
	v_cvt_pk_bf16_f32 v93, v94, v95
	v_cvt_pk_bf16_f32 v94, v88, v89
	v_cvt_pk_bf16_f32 v95, v90, v91
	v_cvt_pk_bf16_f32 v84, v84, v85
	v_cvt_pk_bf16_f32 v85, v86, v87
	v_cvt_pk_bf16_f32 v86, v80, v81
	v_cvt_pk_bf16_f32 v87, v82, v83
	v_add_u32_e32 v140, 0x2c000, v139
	global_store_dwordx4 v140, v[92:95], s[8:9]
	v_add_u32_e32 v141, 0x2c100, v139
	global_store_dwordx4 v141, v[84:87], s[8:9]
	v_pk_mul_f32 v[76:77], v[76:77], v[208:209] op_sel_hi:[1,0]
	v_pk_mul_f32 v[78:79], v[78:79], v[208:209] op_sel_hi:[1,0]
	v_pk_mul_f32 v[72:73], v[72:73], v[208:209] op_sel_hi:[1,0]
	v_pk_mul_f32 v[74:75], v[74:75], v[208:209] op_sel_hi:[1,0]
	v_pk_mul_f32 v[68:69], v[68:69], v[208:209] op_sel_hi:[1,0]
	v_pk_mul_f32 v[70:71], v[70:71], v[208:209] op_sel_hi:[1,0]
	v_pk_mul_f32 v[64:65], v[64:65], v[208:209] op_sel_hi:[1,0]
	v_pk_mul_f32 v[66:67], v[66:67], v[208:209] op_sel_hi:[1,0]
	v_cvt_pk_bf16_f32 v76, v76, v77
	v_cvt_pk_bf16_f32 v77, v78, v79
	v_cvt_pk_bf16_f32 v78, v72, v73
	v_cvt_pk_bf16_f32 v79, v74, v75
	v_cvt_pk_bf16_f32 v68, v68, v69
	v_cvt_pk_bf16_f32 v69, v70, v71
	v_cvt_pk_bf16_f32 v70, v64, v65
	v_cvt_pk_bf16_f32 v71, v66, v67
	v_add_u32_e32 v140, 0x42000, v139
	global_store_dwordx4 v140, v[76:79], s[8:9]
	v_add_u32_e32 v141, 0x42100, v139
	global_store_dwordx4 v141, v[68:71], s[8:9]
	v_pk_mul_f32 v[60:61], v[60:61], v[210:211] op_sel_hi:[1,0]
	v_pk_mul_f32 v[62:63], v[62:63], v[210:211] op_sel_hi:[1,0]
	v_pk_mul_f32 v[56:57], v[56:57], v[210:211] op_sel_hi:[1,0]
	v_pk_mul_f32 v[58:59], v[58:59], v[210:211] op_sel_hi:[1,0]
	v_pk_mul_f32 v[52:53], v[52:53], v[210:211] op_sel_hi:[1,0]
	v_pk_mul_f32 v[54:55], v[54:55], v[210:211] op_sel_hi:[1,0]
	v_pk_mul_f32 v[48:49], v[48:49], v[210:211] op_sel_hi:[1,0]
	v_pk_mul_f32 v[50:51], v[50:51], v[210:211] op_sel_hi:[1,0]
	v_cvt_pk_bf16_f32 v60, v60, v61
	v_cvt_pk_bf16_f32 v61, v62, v63
	v_cvt_pk_bf16_f32 v62, v56, v57
	v_cvt_pk_bf16_f32 v63, v58, v59
	v_cvt_pk_bf16_f32 v52, v52, v53
	v_cvt_pk_bf16_f32 v53, v54, v55
	v_cvt_pk_bf16_f32 v54, v48, v49
	v_cvt_pk_bf16_f32 v55, v50, v51
	v_add_u32_e32 v140, 0xb0000, v139
	global_store_dwordx4 v140, v[60:63], s[8:9]
	v_add_u32_e32 v141, 0xb0100, v139
	global_store_dwordx4 v141, v[52:55], s[8:9]
	v_pk_mul_f32 v[44:45], v[44:45], v[212:213] op_sel_hi:[1,0]
	v_pk_mul_f32 v[46:47], v[46:47], v[212:213] op_sel_hi:[1,0]
	v_pk_mul_f32 v[40:41], v[40:41], v[212:213] op_sel_hi:[1,0]
	v_pk_mul_f32 v[42:43], v[42:43], v[212:213] op_sel_hi:[1,0]
	v_pk_mul_f32 v[36:37], v[36:37], v[212:213] op_sel_hi:[1,0]
	v_pk_mul_f32 v[38:39], v[38:39], v[212:213] op_sel_hi:[1,0]
	v_pk_mul_f32 v[32:33], v[32:33], v[212:213] op_sel_hi:[1,0]
	v_pk_mul_f32 v[34:35], v[34:35], v[212:213] op_sel_hi:[1,0]
	v_cvt_pk_bf16_f32 v44, v44, v45
	v_cvt_pk_bf16_f32 v45, v46, v47
	v_cvt_pk_bf16_f32 v46, v40, v41
	v_cvt_pk_bf16_f32 v47, v42, v43
	v_cvt_pk_bf16_f32 v36, v36, v37
	v_cvt_pk_bf16_f32 v37, v38, v39
	v_cvt_pk_bf16_f32 v38, v32, v33
	v_cvt_pk_bf16_f32 v39, v34, v35
	v_add_u32_e32 v140, 0xc6000, v139
	global_store_dwordx4 v140, v[44:47], s[8:9]
	v_add_u32_e32 v141, 0xc6100, v139
	global_store_dwordx4 v141, v[36:39], s[8:9]
	v_pk_mul_f32 v[28:29], v[28:29], v[214:215] op_sel_hi:[1,0]
	v_pk_mul_f32 v[30:31], v[30:31], v[214:215] op_sel_hi:[1,0]
	v_pk_mul_f32 v[24:25], v[24:25], v[214:215] op_sel_hi:[1,0]
	v_pk_mul_f32 v[26:27], v[26:27], v[214:215] op_sel_hi:[1,0]
	v_pk_mul_f32 v[20:21], v[20:21], v[214:215] op_sel_hi:[1,0]
	v_pk_mul_f32 v[22:23], v[22:23], v[214:215] op_sel_hi:[1,0]
	v_pk_mul_f32 v[16:17], v[16:17], v[214:215] op_sel_hi:[1,0]
	v_pk_mul_f32 v[18:19], v[18:19], v[214:215] op_sel_hi:[1,0]
	v_cvt_pk_bf16_f32 v28, v28, v29
	v_cvt_pk_bf16_f32 v29, v30, v31
	v_cvt_pk_bf16_f32 v30, v24, v25
	v_cvt_pk_bf16_f32 v31, v26, v27
	v_cvt_pk_bf16_f32 v20, v20, v21
	v_cvt_pk_bf16_f32 v21, v22, v23
	v_cvt_pk_bf16_f32 v22, v16, v17
	v_cvt_pk_bf16_f32 v23, v18, v19
	v_add_u32_e32 v140, 0xdc000, v139
	global_store_dwordx4 v140, v[28:31], s[8:9]
	v_add_u32_e32 v141, 0xdc100, v139
	global_store_dwordx4 v141, v[20:23], s[8:9]
	v_pk_mul_f32 v[12:13], v[12:13], v[216:217] op_sel_hi:[1,0]
	v_pk_mul_f32 v[14:15], v[14:15], v[216:217] op_sel_hi:[1,0]
	v_pk_mul_f32 v[8:9], v[8:9], v[216:217] op_sel_hi:[1,0]
	v_pk_mul_f32 v[10:11], v[10:11], v[216:217] op_sel_hi:[1,0]
	v_pk_mul_f32 v[4:5], v[4:5], v[216:217] op_sel_hi:[1,0]
	v_pk_mul_f32 v[6:7], v[6:7], v[216:217] op_sel_hi:[1,0]
	v_pk_mul_f32 v[0:1], v[0:1], v[216:217] op_sel_hi:[1,0]
	v_pk_mul_f32 v[2:3], v[2:3], v[216:217] op_sel_hi:[1,0]
	v_cvt_pk_bf16_f32 v12, v12, v13
	v_cvt_pk_bf16_f32 v13, v14, v15
	v_cvt_pk_bf16_f32 v14, v8, v9
	v_cvt_pk_bf16_f32 v15, v10, v11
	v_cvt_pk_bf16_f32 v4, v4, v5
	v_cvt_pk_bf16_f32 v5, v6, v7
	v_cvt_pk_bf16_f32 v6, v0, v1
	v_cvt_pk_bf16_f32 v7, v2, v3
	v_add_u32_e32 v140, 0xf2000, v139
	global_store_dwordx4 v140, v[12:15], s[8:9]
	v_add_u32_e32 v141, 0xf2100, v139
	global_store_dwordx4 v141, v[4:7], s[8:9]
	s_branch .LBB0_1021
; __device__ __forceinline__ unsigned pk2(float lo, float hi) { return pg8::cvt_pk_bf16(lo, hi); }
; __device__ __forceinline__ float sigmoidf_(float x) { return __builtin_amdgcn_rcpf(1.0f + __expf(-x)); }
; __device__ __forceinline__ float geluf_(float x) { const float z = 1.5957691216057308f * (x + 0.044715f * x * x * x); return x * sigmoidf_(z); }
; __device__ __forceinline__ float siluf_(float x) { return x * sigmoidf_(x); }
;     __device__ __forceinline__ void operator()(const f32x4 (&acc)[2][2][4][2], const pg8::Unit& u, int wr, int wc, int fr, int fq) const {
;     ...
;             for (int ai = 0; ai < 2; ++ai)
; #pragma unroll
;                 for (int m = 0; m < 4; ++m) {
;                     const int row = row0 + ai * 128 + m * 16; const float r = rs[ai * 4 + m];
; #pragma unroll
;                     for (int bj = 0; bj < 2; ++bj) {
;                         float v[8];
; #pragma unroll
;                         for (int n = 0; n < 2; ++n)
; #pragma unroll
;                             for (int j = 0; j < 4; ++j) { float t = acc[ai][bj][m][n][j] * r; if (act == 1) t = siluf_(t); else if (act == 2) t = geluf_(t); v[n * 4 + j] = t; }
;                         u32x4 w; w.x = pk2(v[0], v[1]); w.y = pk2(v[2], v[3]); w.z = pk2(v[4], v[5]); w.w = pk2(v[6], v[7]);
;                         *(u32x4*)(Z + (size_t)row * IW + pn * 256 + bj * 128 + wc * 32 + 8 * fq) = w;
;                     }
.Lwin_act_silu:
	v_pk_mul_f32 v[124:125], v[124:125], v[202:203] op_sel_hi:[1,0]
	v_pk_mul_f32 v[126:127], v[126:127], v[202:203] op_sel_hi:[1,0]
	v_pk_mul_f32 v[120:121], v[120:121], v[202:203] op_sel_hi:[1,0]
	v_pk_mul_f32 v[122:123], v[122:123], v[202:203] op_sel_hi:[1,0]
	v_pk_mul_f32 v[116:117], v[116:117], v[202:203] op_sel_hi:[1,0]
	v_pk_mul_f32 v[118:119], v[118:119], v[202:203] op_sel_hi:[1,0]
	v_pk_mul_f32 v[112:113], v[112:113], v[202:203] op_sel_hi:[1,0]
	v_pk_mul_f32 v[114:115], v[114:115], v[202:203] op_sel_hi:[1,0]
	v_pk_mul_f32 v[218:219], v[124:125], v[132:133] op_sel_hi:[1,0]
	v_pk_mul_f32 v[220:221], v[126:127], v[132:133] op_sel_hi:[1,0]
	v_pk_mul_f32 v[222:223], v[120:121], v[132:133] op_sel_hi:[1,0]
	v_pk_mul_f32 v[224:225], v[122:123], v[132:133] op_sel_hi:[1,0]
	v_pk_mul_f32 v[226:227], v[116:117], v[132:133] op_sel_hi:[1,0]
	v_pk_mul_f32 v[228:229], v[118:119], v[132:133] op_sel_hi:[1,0]
	v_pk_mul_f32 v[230:231], v[112:113], v[132:133] op_sel_hi:[1,0]
	v_pk_mul_f32 v[232:233], v[114:115], v[132:133] op_sel_hi:[1,0]
	v_exp_f32_e32 v218, v218
	v_exp_f32_e32 v219, v219
	v_exp_f32_e32 v220, v220
	v_exp_f32_e32 v221, v221
	v_exp_f32_e32 v222, v222
	v_exp_f32_e32 v223, v223
	v_exp_f32_e32 v224, v224
	v_exp_f32_e32 v225, v225
	v_exp_f32_e32 v226, v226
	v_exp_f32_e32 v227, v227
	v_exp_f32_e32 v228, v228
	v_exp_f32_e32 v229, v229
	v_exp_f32_e32 v230, v230
	v_exp_f32_e32 v231, v231
	v_exp_f32_e32 v232, v232
	v_exp_f32_e32 v233, v233
	v_pk_add_f32 v[218:219], v[218:219], v[128:129]
	v_pk_add_f32 v[220:221], v[220:221], v[128:129]
	v_pk_add_f32 v[222:223], v[222:223], v[128:129]
	v_pk_add_f32 v[224:225], v[224:225], v[128:129]
	v_pk_add_f32 v[226:227], v[226:227], v[128:129]
	v_pk_add_f32 v[228:229], v[228:229], v[128:129]
	v_pk_add_f32 v[230:231], v[230:231], v[128:129]
	v_pk_add_f32 v[232:233], v[232:233], v[128:129]
	v_rcp_f32_e32 v218, v218
	v_rcp_f32_e32 v219, v219
	v_rcp_f32_e32 v220, v220
	v_rcp_f32_e32 v221, v221
	v_rcp_f32_e32 v222, v222
	v_rcp_f32_e32 v223, v223
	v_rcp_f32_e32 v224, v224
	v_rcp_f32_e32 v225, v225
	v_rcp_f32_e32 v226, v226
	v_rcp_f32_e32 v227, v227
	v_rcp_f32_e32 v228, v228
	v_rcp_f32_e32 v229, v229
	v_rcp_f32_e32 v230, v230
	v_rcp_f32_e32 v231, v231
	v_rcp_f32_e32 v232, v232
	v_rcp_f32_e32 v233, v233
	v_pk_mul_f32 v[124:125], v[124:125], v[218:219]
	v_pk_mul_f32 v[126:127], v[126:127], v[220:221]
	v_pk_mul_f32 v[120:121], v[120:121], v[222:223]
	v_pk_mul_f32 v[122:123], v[122:123], v[224:225]
	v_pk_mul_f32 v[116:117], v[116:117], v[226:227]
	v_pk_mul_f32 v[118:119], v[118:119], v[228:229]
	v_pk_mul_f32 v[112:113], v[112:113], v[230:231]
	v_pk_mul_f32 v[114:115], v[114:115], v[232:233]
	v_cvt_pk_bf16_f32 v124, v124, v125
	v_cvt_pk_bf16_f32 v125, v126, v127
	v_cvt_pk_bf16_f32 v126, v120, v121
	v_cvt_pk_bf16_f32 v127, v122, v123
	v_cvt_pk_bf16_f32 v116, v116, v117
	v_cvt_pk_bf16_f32 v117, v118, v119
	v_cvt_pk_bf16_f32 v118, v112, v113
	v_cvt_pk_bf16_f32 v119, v114, v115
	v_mov_b32_e32 v140, v139
	global_store_dwordx4 v140, v[124:127], s[8:9]
	v_add_u32_e32 v141, 0x100, v139
	global_store_dwordx4 v141, v[116:119], s[8:9]
	v_pk_mul_f32 v[108:109], v[108:109], v[204:205] op_sel_hi:[1,0]
	v_pk_mul_f32 v[110:111], v[110:111], v[204:205] op_sel_hi:[1,0]
	v_pk_mul_f32 v[104:105], v[104:105], v[204:205] op_sel_hi:[1,0]
	v_pk_mul_f32 v[106:107], v[106:107], v[204:205] op_sel_hi:[1,0]
	v_pk_mul_f32 v[100:101], v[100:101], v[204:205] op_sel_hi:[1,0]
	v_pk_mul_f32 v[102:103], v[102:103], v[204:205] op_sel_hi:[1,0]
	v_pk_mul_f32 v[96:97], v[96:97], v[204:205] op_sel_hi:[1,0]
	v_pk_mul_f32 v[98:99], v[98:99], v[204:205] op_sel_hi:[1,0]
	v_pk_mul_f32 v[218:219], v[108:109], v[132:133] op_sel_hi:[1,0]
	v_pk_mul_f32 v[220:221], v[110:111], v[132:133] op_sel_hi:[1,0]
	v_pk_mul_f32 v[222:223], v[104:105], v[132:133] op_sel_hi:[1,0]
	v_pk_mul_f32 v[224:225], v[106:107], v[132:133] op_sel_hi:[1,0]
	v_pk_mul_f32 v[226:227], v[100:101], v[132:133] op_sel_hi:[1,0]
	v_pk_mul_f32 v[228:229], v[102:103], v[132:133] op_sel_hi:[1,0]
	v_pk_mul_f32 v[230:231], v[96:97], v[132:133] op_sel_hi:[1,0]
	v_pk_mul_f32 v[232:233], v[98:99], v[132:133] op_sel_hi:[1,0]
	v_exp_f32_e32 v218, v218
	v_exp_f32_e32 v219, v219
	v_exp_f32_e32 v220, v220
	v_exp_f32_e32 v221, v221
	v_exp_f32_e32 v222, v222
	v_exp_f32_e32 v223, v223
	v_exp_f32_e32 v224, v224
	v_exp_f32_e32 v225, v225
	v_exp_f32_e32 v226, v226
	v_exp_f32_e32 v227, v227
	v_exp_f32_e32 v228, v228
	v_exp_f32_e32 v229, v229
	v_exp_f32_e32 v230, v230
	v_exp_f32_e32 v231, v231
	v_exp_f32_e32 v232, v232
	v_exp_f32_e32 v233, v233
	v_pk_add_f32 v[218:219], v[218:219], v[128:129]
	v_pk_add_f32 v[220:221], v[220:221], v[128:129]
	v_pk_add_f32 v[222:223], v[222:223], v[128:129]
	v_pk_add_f32 v[224:225], v[224:225], v[128:129]
	v_pk_add_f32 v[226:227], v[226:227], v[128:129]
	v_pk_add_f32 v[228:229], v[228:229], v[128:129]
	v_pk_add_f32 v[230:231], v[230:231], v[128:129]
	v_pk_add_f32 v[232:233], v[232:233], v[128:129]
	v_rcp_f32_e32 v218, v218
	v_rcp_f32_e32 v219, v219
	v_rcp_f32_e32 v220, v220
	v_rcp_f32_e32 v221, v221
	v_rcp_f32_e32 v222, v222
	v_rcp_f32_e32 v223, v223
	v_rcp_f32_e32 v224, v224
	v_rcp_f32_e32 v225, v225
	v_rcp_f32_e32 v226, v226
	v_rcp_f32_e32 v227, v227
	v_rcp_f32_e32 v228, v228
	v_rcp_f32_e32 v229, v229
	v_rcp_f32_e32 v230, v230
	v_rcp_f32_e32 v231, v231
	v_rcp_f32_e32 v232, v232
	v_rcp_f32_e32 v233, v233
	v_pk_mul_f32 v[108:109], v[108:109], v[218:219]
	v_pk_mul_f32 v[110:111], v[110:111], v[220:221]
	v_pk_mul_f32 v[104:105], v[104:105], v[222:223]
	v_pk_mul_f32 v[106:107], v[106:107], v[224:225]
	v_pk_mul_f32 v[100:101], v[100:101], v[226:227]
	v_pk_mul_f32 v[102:103], v[102:103], v[228:229]
; __device__ __forceinline__ unsigned pk2(float lo, float hi) { return pg8::cvt_pk_bf16(lo, hi); }
; __device__ __forceinline__ float siluf_(float x) { return x * sigmoidf_(x); }
; __device__ __forceinline__ float geluf_(float x) { const float z = 1.5957691216057308f * (x + 0.044715f * x * x * x); return x * sigmoidf_(z); }
;     __device__ __forceinline__ void operator()(const f32x4 (&acc)[2][2][4][2], const pg8::Unit& u, int wr, int wc, int fr, int fq) const {
;     ...
;             for (int ai = 0; ai < 2; ++ai)
; #pragma unroll
;                 for (int m = 0; m < 4; ++m) {
;                     const int row = row0 + ai * 128 + m * 16; const float r = rs[ai * 4 + m];
; #pragma unroll
;                     for (int bj = 0; bj < 2; ++bj) {
;                         float v[8];
; #pragma unroll
;                         for (int n = 0; n < 2; ++n)
; #pragma unroll
;                             for (int j = 0; j < 4; ++j) { float t = acc[ai][bj][m][n][j] * r; if (act == 1) t = siluf_(t); else if (act == 2) t = geluf_(t); v[n * 4 + j] = t; }
;                         u32x4 w; w.x = pk2(v[0], v[1]); w.y = pk2(v[2], v[3]); w.z = pk2(v[4], v[5]); w.w = pk2(v[6], v[7]);
;                         *(u32x4*)(Z + (size_t)row * IW + pn * 256 + bj * 128 + wc * 32 + 8 * fq) = w;
;                     }
	v_pk_mul_f32 v[96:97], v[96:97], v[230:231]
	v_pk_mul_f32 v[98:99], v[98:99], v[232:233]
	v_cvt_pk_bf16_f32 v108, v108, v109
	v_cvt_pk_bf16_f32 v109, v110, v111
	v_cvt_pk_bf16_f32 v110, v104, v105
	v_cvt_pk_bf16_f32 v111, v106, v107
	v_cvt_pk_bf16_f32 v100, v100, v101
	v_cvt_pk_bf16_f32 v101, v102, v103
	v_cvt_pk_bf16_f32 v102, v96, v97
	v_cvt_pk_bf16_f32 v103, v98, v99
	v_add_u32_e32 v140, 0x16000, v139
	global_store_dwordx4 v140, v[108:111], s[8:9]
	v_add_u32_e32 v141, 0x16100, v139
	global_store_dwordx4 v141, v[100:103], s[8:9]
	v_pk_mul_f32 v[92:93], v[92:93], v[206:207] op_sel_hi:[1,0]
	v_pk_mul_f32 v[94:95], v[94:95], v[206:207] op_sel_hi:[1,0]
	v_pk_mul_f32 v[88:89], v[88:89], v[206:207] op_sel_hi:[1,0]
	v_pk_mul_f32 v[90:91], v[90:91], v[206:207] op_sel_hi:[1,0]
	v_pk_mul_f32 v[84:85], v[84:85], v[206:207] op_sel_hi:[1,0]
	v_pk_mul_f32 v[86:87], v[86:87], v[206:207] op_sel_hi:[1,0]
	v_pk_mul_f32 v[80:81], v[80:81], v[206:207] op_sel_hi:[1,0]
	v_pk_mul_f32 v[82:83], v[82:83], v[206:207] op_sel_hi:[1,0]
	v_pk_mul_f32 v[218:219], v[92:93], v[132:133] op_sel_hi:[1,0]
	v_pk_mul_f32 v[220:221], v[94:95], v[132:133] op_sel_hi:[1,0]
	v_pk_mul_f32 v[222:223], v[88:89], v[132:133] op_sel_hi:[1,0]
	v_pk_mul_f32 v[224:225], v[90:91], v[132:133] op_sel_hi:[1,0]
	v_pk_mul_f32 v[226:227], v[84:85], v[132:133] op_sel_hi:[1,0]
	v_pk_mul_f32 v[228:229], v[86:87], v[132:133] op_sel_hi:[1,0]
	v_pk_mul_f32 v[230:231], v[80:81], v[132:133] op_sel_hi:[1,0]
	v_pk_mul_f32 v[232:233], v[82:83], v[132:133] op_sel_hi:[1,0]
	v_exp_f32_e32 v218, v218
	v_exp_f32_e32 v219, v219
	v_exp_f32_e32 v220, v220
	v_exp_f32_e32 v221, v221
	v_exp_f32_e32 v222, v222
	v_exp_f32_e32 v223, v223
	v_exp_f32_e32 v224, v224
	v_exp_f32_e32 v225, v225
	v_exp_f32_e32 v226, v226
	v_exp_f32_e32 v227, v227
	v_exp_f32_e32 v228, v228
	v_exp_f32_e32 v229, v229
	v_exp_f32_e32 v230, v230
	v_exp_f32_e32 v231, v231
	v_exp_f32_e32 v232, v232
	v_exp_f32_e32 v233, v233
	v_pk_add_f32 v[218:219], v[218:219], v[128:129]
	v_pk_add_f32 v[220:221], v[220:221], v[128:129]
	v_pk_add_f32 v[222:223], v[222:223], v[128:129]
	v_pk_add_f32 v[224:225], v[224:225], v[128:129]
	v_pk_add_f32 v[226:227], v[226:227], v[128:129]
	v_pk_add_f32 v[228:229], v[228:229], v[128:129]
	v_pk_add_f32 v[230:231], v[230:231], v[128:129]
	v_pk_add_f32 v[232:233], v[232:233], v[128:129]
	v_rcp_f32_e32 v218, v218
	v_rcp_f32_e32 v219, v219
	v_rcp_f32_e32 v220, v220
	v_rcp_f32_e32 v221, v221
	v_rcp_f32_e32 v222, v222
	v_rcp_f32_e32 v223, v223
	v_rcp_f32_e32 v224, v224
	v_rcp_f32_e32 v225, v225
	v_rcp_f32_e32 v226, v226
	v_rcp_f32_e32 v227, v227
	v_rcp_f32_e32 v228, v228
	v_rcp_f32_e32 v229, v229
	v_rcp_f32_e32 v230, v230
	v_rcp_f32_e32 v231, v231
	v_rcp_f32_e32 v232, v232
	v_rcp_f32_e32 v233, v233
	v_pk_mul_f32 v[92:93], v[92:93], v[218:219]
	v_pk_mul_f32 v[94:95], v[94:95], v[220:221]
	v_pk_mul_f32 v[88:89], v[88:89], v[222:223]
	v_pk_mul_f32 v[90:91], v[90:91], v[224:225]
	v_pk_mul_f32 v[84:85], v[84:85], v[226:227]
	v_pk_mul_f32 v[86:87], v[86:87], v[228:229]
	v_pk_mul_f32 v[80:81], v[80:81], v[230:231]
	v_pk_mul_f32 v[82:83], v[82:83], v[232:233]
	v_cvt_pk_bf16_f32 v92, v92, v93
	v_cvt_pk_bf16_f32 v93, v94, v95
	v_cvt_pk_bf16_f32 v94, v88, v89
	v_cvt_pk_bf16_f32 v95, v90, v91
	v_cvt_pk_bf16_f32 v84, v84, v85
	v_cvt_pk_bf16_f32 v85, v86, v87
	v_cvt_pk_bf16_f32 v86, v80, v81
	v_cvt_pk_bf16_f32 v87, v82, v83
	v_add_u32_e32 v140, 0x2c000, v139
	global_store_dwordx4 v140, v[92:95], s[8:9]
	v_add_u32_e32 v141, 0x2c100, v139
	global_store_dwordx4 v141, v[84:87], s[8:9]
	v_pk_mul_f32 v[76:77], v[76:77], v[208:209] op_sel_hi:[1,0]
	v_pk_mul_f32 v[78:79], v[78:79], v[208:209] op_sel_hi:[1,0]
	v_pk_mul_f32 v[72:73], v[72:73], v[208:209] op_sel_hi:[1,0]
	v_pk_mul_f32 v[74:75], v[74:75], v[208:209] op_sel_hi:[1,0]
	v_pk_mul_f32 v[68:69], v[68:69], v[208:209] op_sel_hi:[1,0]
	v_pk_mul_f32 v[70:71], v[70:71], v[208:209] op_sel_hi:[1,0]
	v_pk_mul_f32 v[64:65], v[64:65], v[208:209] op_sel_hi:[1,0]
	v_pk_mul_f32 v[66:67], v[66:67], v[208:209] op_sel_hi:[1,0]
	v_pk_mul_f32 v[218:219], v[76:77], v[132:133] op_sel_hi:[1,0]
	v_pk_mul_f32 v[220:221], v[78:79], v[132:133] op_sel_hi:[1,0]
	v_pk_mul_f32 v[222:223], v[72:73], v[132:133] op_sel_hi:[1,0]
	v_pk_mul_f32 v[224:225], v[74:75], v[132:133] op_sel_hi:[1,0]
	v_pk_mul_f32 v[226:227], v[68:69], v[132:133] op_sel_hi:[1,0]
	v_pk_mul_f32 v[228:229], v[70:71], v[132:133] op_sel_hi:[1,0]
	v_pk_mul_f32 v[230:231], v[64:65], v[132:133] op_sel_hi:[1,0]
	v_pk_mul_f32 v[232:233], v[66:67], v[132:133] op_sel_hi:[1,0]
	v_exp_f32_e32 v218, v218
	v_exp_f32_e32 v219, v219
	v_exp_f32_e32 v220, v220
	v_exp_f32_e32 v221, v221
	v_exp_f32_e32 v222, v222
	v_exp_f32_e32 v223, v223
	v_exp_f32_e32 v224, v224
	v_exp_f32_e32 v225, v225
	v_exp_f32_e32 v226, v226
	v_exp_f32_e32 v227, v227
	v_exp_f32_e32 v228, v228
	v_exp_f32_e32 v229, v229
	v_exp_f32_e32 v230, v230
	v_exp_f32_e32 v231, v231
	v_exp_f32_e32 v232, v232
	v_exp_f32_e32 v233, v233
	v_pk_add_f32 v[218:219], v[218:219], v[128:129]
	v_pk_add_f32 v[220:221], v[220:221], v[128:129]
	v_pk_add_f32 v[222:223], v[222:223], v[128:129]
	v_pk_add_f32 v[224:225], v[224:225], v[128:129]
	v_pk_add_f32 v[226:227], v[226:227], v[128:129]
	v_pk_add_f32 v[228:229], v[228:229], v[128:129]
	v_pk_add_f32 v[230:231], v[230:231], v[128:129]
	v_pk_add_f32 v[232:233], v[232:233], v[128:129]
	v_rcp_f32_e32 v218, v218
	v_rcp_f32_e32 v219, v219
	v_rcp_f32_e32 v220, v220
	v_rcp_f32_e32 v221, v221
	v_rcp_f32_e32 v222, v222
	v_rcp_f32_e32 v223, v223
	v_rcp_f32_e32 v224, v224
	v_rcp_f32_e32 v225, v225
	v_rcp_f32_e32 v226, v226
	v_rcp_f32_e32 v227, v227
	v_rcp_f32_e32 v228, v228
	v_rcp_f32_e32 v229, v229
; __device__ __forceinline__ unsigned pk2(float lo, float hi) { return pg8::cvt_pk_bf16(lo, hi); }
; __device__ __forceinline__ float siluf_(float x) { return x * sigmoidf_(x); }
; __device__ __forceinline__ float geluf_(float x) { const float z = 1.5957691216057308f * (x + 0.044715f * x * x * x); return x * sigmoidf_(z); }
;     __device__ __forceinline__ void operator()(const f32x4 (&acc)[2][2][4][2], const pg8::Unit& u, int wr, int wc, int fr, int fq) const {
;     ...
;             for (int ai = 0; ai < 2; ++ai)
; #pragma unroll
;                 for (int m = 0; m < 4; ++m) {
;                     const int row = row0 + ai * 128 + m * 16; const float r = rs[ai * 4 + m];
; #pragma unroll
;                     for (int bj = 0; bj < 2; ++bj) {
;                         float v[8];
; #pragma unroll
;                         for (int n = 0; n < 2; ++n)
; #pragma unroll
;                             for (int j = 0; j < 4; ++j) { float t = acc[ai][bj][m][n][j] * r; if (act == 1) t = siluf_(t); else if (act == 2) t = geluf_(t); v[n * 4 + j] = t; }
;                         u32x4 w; w.x = pk2(v[0], v[1]); w.y = pk2(v[2], v[3]); w.z = pk2(v[4], v[5]); w.w = pk2(v[6], v[7]);
;                         *(u32x4*)(Z + (size_t)row * IW + pn * 256 + bj * 128 + wc * 32 + 8 * fq) = w;
;                     }
	v_rcp_f32_e32 v230, v230
	v_rcp_f32_e32 v231, v231
	v_rcp_f32_e32 v232, v232
	v_rcp_f32_e32 v233, v233
	v_pk_mul_f32 v[76:77], v[76:77], v[218:219]
	v_pk_mul_f32 v[78:79], v[78:79], v[220:221]
	v_pk_mul_f32 v[72:73], v[72:73], v[222:223]
	v_pk_mul_f32 v[74:75], v[74:75], v[224:225]
	v_pk_mul_f32 v[68:69], v[68:69], v[226:227]
	v_pk_mul_f32 v[70:71], v[70:71], v[228:229]
	v_pk_mul_f32 v[64:65], v[64:65], v[230:231]
	v_pk_mul_f32 v[66:67], v[66:67], v[232:233]
	v_cvt_pk_bf16_f32 v76, v76, v77
	v_cvt_pk_bf16_f32 v77, v78, v79
	v_cvt_pk_bf16_f32 v78, v72, v73
	v_cvt_pk_bf16_f32 v79, v74, v75
	v_cvt_pk_bf16_f32 v68, v68, v69
	v_cvt_pk_bf16_f32 v69, v70, v71
	v_cvt_pk_bf16_f32 v70, v64, v65
	v_cvt_pk_bf16_f32 v71, v66, v67
	v_add_u32_e32 v140, 0x42000, v139
	global_store_dwordx4 v140, v[76:79], s[8:9]
	v_add_u32_e32 v141, 0x42100, v139
	global_store_dwordx4 v141, v[68:71], s[8:9]
	v_pk_mul_f32 v[60:61], v[60:61], v[210:211] op_sel_hi:[1,0]
	v_pk_mul_f32 v[62:63], v[62:63], v[210:211] op_sel_hi:[1,0]
	v_pk_mul_f32 v[56:57], v[56:57], v[210:211] op_sel_hi:[1,0]
	v_pk_mul_f32 v[58:59], v[58:59], v[210:211] op_sel_hi:[1,0]
	v_pk_mul_f32 v[52:53], v[52:53], v[210:211] op_sel_hi:[1,0]
	v_pk_mul_f32 v[54:55], v[54:55], v[210:211] op_sel_hi:[1,0]
	v_pk_mul_f32 v[48:49], v[48:49], v[210:211] op_sel_hi:[1,0]
	v_pk_mul_f32 v[50:51], v[50:51], v[210:211] op_sel_hi:[1,0]
	v_pk_mul_f32 v[218:219], v[60:61], v[132:133] op_sel_hi:[1,0]
	v_pk_mul_f32 v[220:221], v[62:63], v[132:133] op_sel_hi:[1,0]
	v_pk_mul_f32 v[222:223], v[56:57], v[132:133] op_sel_hi:[1,0]
	v_pk_mul_f32 v[224:225], v[58:59], v[132:133] op_sel_hi:[1,0]
	v_pk_mul_f32 v[226:227], v[52:53], v[132:133] op_sel_hi:[1,0]
	v_pk_mul_f32 v[228:229], v[54:55], v[132:133] op_sel_hi:[1,0]
	v_pk_mul_f32 v[230:231], v[48:49], v[132:133] op_sel_hi:[1,0]
	v_pk_mul_f32 v[232:233], v[50:51], v[132:133] op_sel_hi:[1,0]
	v_exp_f32_e32 v218, v218
	v_exp_f32_e32 v219, v219
	v_exp_f32_e32 v220, v220
	v_exp_f32_e32 v221, v221
	v_exp_f32_e32 v222, v222
	v_exp_f32_e32 v223, v223
	v_exp_f32_e32 v224, v224
	v_exp_f32_e32 v225, v225
	v_exp_f32_e32 v226, v226
	v_exp_f32_e32 v227, v227
	v_exp_f32_e32 v228, v228
	v_exp_f32_e32 v229, v229
	v_exp_f32_e32 v230, v230
	v_exp_f32_e32 v231, v231
	v_exp_f32_e32 v232, v232
	v_exp_f32_e32 v233, v233
	v_pk_add_f32 v[218:219], v[218:219], v[128:129]
	v_pk_add_f32 v[220:221], v[220:221], v[128:129]
	v_pk_add_f32 v[222:223], v[222:223], v[128:129]
	v_pk_add_f32 v[224:225], v[224:225], v[128:129]
	v_pk_add_f32 v[226:227], v[226:227], v[128:129]
	v_pk_add_f32 v[228:229], v[228:229], v[128:129]
	v_pk_add_f32 v[230:231], v[230:231], v[128:129]
	v_pk_add_f32 v[232:233], v[232:233], v[128:129]
	v_rcp_f32_e32 v218, v218
	v_rcp_f32_e32 v219, v219
	v_rcp_f32_e32 v220, v220
	v_rcp_f32_e32 v221, v221
	v_rcp_f32_e32 v222, v222
	v_rcp_f32_e32 v223, v223
	v_rcp_f32_e32 v224, v224
	v_rcp_f32_e32 v225, v225
	v_rcp_f32_e32 v226, v226
	v_rcp_f32_e32 v227, v227
	v_rcp_f32_e32 v228, v228
	v_rcp_f32_e32 v229, v229
	v_rcp_f32_e32 v230, v230
	v_rcp_f32_e32 v231, v231
	v_rcp_f32_e32 v232, v232
	v_rcp_f32_e32 v233, v233
	v_pk_mul_f32 v[60:61], v[60:61], v[218:219]
	v_pk_mul_f32 v[62:63], v[62:63], v[220:221]
	v_pk_mul_f32 v[56:57], v[56:57], v[222:223]
	v_pk_mul_f32 v[58:59], v[58:59], v[224:225]
	v_pk_mul_f32 v[52:53], v[52:53], v[226:227]
	v_pk_mul_f32 v[54:55], v[54:55], v[228:229]
	v_pk_mul_f32 v[48:49], v[48:49], v[230:231]
	v_pk_mul_f32 v[50:51], v[50:51], v[232:233]
	v_cvt_pk_bf16_f32 v60, v60, v61
	v_cvt_pk_bf16_f32 v61, v62, v63
	v_cvt_pk_bf16_f32 v62, v56, v57
	v_cvt_pk_bf16_f32 v63, v58, v59
	v_cvt_pk_bf16_f32 v52, v52, v53
	v_cvt_pk_bf16_f32 v53, v54, v55
	v_cvt_pk_bf16_f32 v54, v48, v49
	v_cvt_pk_bf16_f32 v55, v50, v51
	v_add_u32_e32 v140, 0xb0000, v139
	global_store_dwordx4 v140, v[60:63], s[8:9]
	v_add_u32_e32 v141, 0xb0100, v139
	global_store_dwordx4 v141, v[52:55], s[8:9]
	v_pk_mul_f32 v[44:45], v[44:45], v[212:213] op_sel_hi:[1,0]
	v_pk_mul_f32 v[46:47], v[46:47], v[212:213] op_sel_hi:[1,0]
	v_pk_mul_f32 v[40:41], v[40:41], v[212:213] op_sel_hi:[1,0]
	v_pk_mul_f32 v[42:43], v[42:43], v[212:213] op_sel_hi:[1,0]
	v_pk_mul_f32 v[36:37], v[36:37], v[212:213] op_sel_hi:[1,0]
	v_pk_mul_f32 v[38:39], v[38:39], v[212:213] op_sel_hi:[1,0]
	v_pk_mul_f32 v[32:33], v[32:33], v[212:213] op_sel_hi:[1,0]
	v_pk_mul_f32 v[34:35], v[34:35], v[212:213] op_sel_hi:[1,0]
	v_pk_mul_f32 v[218:219], v[44:45], v[132:133] op_sel_hi:[1,0]
	v_pk_mul_f32 v[220:221], v[46:47], v[132:133] op_sel_hi:[1,0]
	v_pk_mul_f32 v[222:223], v[40:41], v[132:133] op_sel_hi:[1,0]
	v_pk_mul_f32 v[224:225], v[42:43], v[132:133] op_sel_hi:[1,0]
	v_pk_mul_f32 v[226:227], v[36:37], v[132:133] op_sel_hi:[1,0]
	v_pk_mul_f32 v[228:229], v[38:39], v[132:133] op_sel_hi:[1,0]
	v_pk_mul_f32 v[230:231], v[32:33], v[132:133] op_sel_hi:[1,0]
	v_pk_mul_f32 v[232:233], v[34:35], v[132:133] op_sel_hi:[1,0]
	v_exp_f32_e32 v218, v218
	v_exp_f32_e32 v219, v219
	v_exp_f32_e32 v220, v220
	v_exp_f32_e32 v221, v221
	v_exp_f32_e32 v222, v222
	v_exp_f32_e32 v223, v223
	v_exp_f32_e32 v224, v224
	v_exp_f32_e32 v225, v225
	v_exp_f32_e32 v226, v226
	v_exp_f32_e32 v227, v227
	v_exp_f32_e32 v228, v228
	v_exp_f32_e32 v229, v229
	v_exp_f32_e32 v230, v230
	v_exp_f32_e32 v231, v231
	v_exp_f32_e32 v232, v232
	v_exp_f32_e32 v233, v233
	v_pk_add_f32 v[218:219], v[218:219], v[128:129]
	v_pk_add_f32 v[220:221], v[220:221], v[128:129]
	v_pk_add_f32 v[222:223], v[222:223], v[128:129]
	v_pk_add_f32 v[224:225], v[224:225], v[128:129]
	v_pk_add_f32 v[226:227], v[226:227], v[128:129]
	v_pk_add_f32 v[228:229], v[228:229], v[128:129]
	v_pk_add_f32 v[230:231], v[230:231], v[128:129]
; __device__ __forceinline__ unsigned pk2(float lo, float hi) { return pg8::cvt_pk_bf16(lo, hi); }
; __device__ __forceinline__ float siluf_(float x) { return x * sigmoidf_(x); }
; __device__ __forceinline__ float geluf_(float x) { const float z = 1.5957691216057308f * (x + 0.044715f * x * x * x); return x * sigmoidf_(z); }
;     __device__ __forceinline__ void operator()(const f32x4 (&acc)[2][2][4][2], const pg8::Unit& u, int wr, int wc, int fr, int fq) const {
;     ...
;             for (int ai = 0; ai < 2; ++ai)
; #pragma unroll
;                 for (int m = 0; m < 4; ++m) {
;                     const int row = row0 + ai * 128 + m * 16; const float r = rs[ai * 4 + m];
; #pragma unroll
;                     for (int bj = 0; bj < 2; ++bj) {
;                         float v[8];
; #pragma unroll
;                         for (int n = 0; n < 2; ++n)
; #pragma unroll
;                             for (int j = 0; j < 4; ++j) { float t = acc[ai][bj][m][n][j] * r; if (act == 1) t = siluf_(t); else if (act == 2) t = geluf_(t); v[n * 4 + j] = t; }
;                         u32x4 w; w.x = pk2(v[0], v[1]); w.y = pk2(v[2], v[3]); w.z = pk2(v[4], v[5]); w.w = pk2(v[6], v[7]);
;                         *(u32x4*)(Z + (size_t)row * IW + pn * 256 + bj * 128 + wc * 32 + 8 * fq) = w;
;                     }
	v_pk_add_f32 v[232:233], v[232:233], v[128:129]
	v_rcp_f32_e32 v218, v218
	v_rcp_f32_e32 v219, v219
	v_rcp_f32_e32 v220, v220
	v_rcp_f32_e32 v221, v221
	v_rcp_f32_e32 v222, v222
	v_rcp_f32_e32 v223, v223
	v_rcp_f32_e32 v224, v224
	v_rcp_f32_e32 v225, v225
	v_rcp_f32_e32 v226, v226
	v_rcp_f32_e32 v227, v227
	v_rcp_f32_e32 v228, v228
	v_rcp_f32_e32 v229, v229
	v_rcp_f32_e32 v230, v230
	v_rcp_f32_e32 v231, v231
	v_rcp_f32_e32 v232, v232
	v_rcp_f32_e32 v233, v233
	v_pk_mul_f32 v[44:45], v[44:45], v[218:219]
	v_pk_mul_f32 v[46:47], v[46:47], v[220:221]
	v_pk_mul_f32 v[40:41], v[40:41], v[222:223]
	v_pk_mul_f32 v[42:43], v[42:43], v[224:225]
	v_pk_mul_f32 v[36:37], v[36:37], v[226:227]
	v_pk_mul_f32 v[38:39], v[38:39], v[228:229]
	v_pk_mul_f32 v[32:33], v[32:33], v[230:231]
	v_pk_mul_f32 v[34:35], v[34:35], v[232:233]
	v_cvt_pk_bf16_f32 v44, v44, v45
	v_cvt_pk_bf16_f32 v45, v46, v47
	v_cvt_pk_bf16_f32 v46, v40, v41
	v_cvt_pk_bf16_f32 v47, v42, v43
	v_cvt_pk_bf16_f32 v36, v36, v37
	v_cvt_pk_bf16_f32 v37, v38, v39
	v_cvt_pk_bf16_f32 v38, v32, v33
	v_cvt_pk_bf16_f32 v39, v34, v35
	v_add_u32_e32 v140, 0xc6000, v139
	global_store_dwordx4 v140, v[44:47], s[8:9]
	v_add_u32_e32 v141, 0xc6100, v139
	global_store_dwordx4 v141, v[36:39], s[8:9]
	v_pk_mul_f32 v[28:29], v[28:29], v[214:215] op_sel_hi:[1,0]
	v_pk_mul_f32 v[30:31], v[30:31], v[214:215] op_sel_hi:[1,0]
	v_pk_mul_f32 v[24:25], v[24:25], v[214:215] op_sel_hi:[1,0]
	v_pk_mul_f32 v[26:27], v[26:27], v[214:215] op_sel_hi:[1,0]
	v_pk_mul_f32 v[20:21], v[20:21], v[214:215] op_sel_hi:[1,0]
	v_pk_mul_f32 v[22:23], v[22:23], v[214:215] op_sel_hi:[1,0]
	v_pk_mul_f32 v[16:17], v[16:17], v[214:215] op_sel_hi:[1,0]
	v_pk_mul_f32 v[18:19], v[18:19], v[214:215] op_sel_hi:[1,0]
	v_pk_mul_f32 v[218:219], v[28:29], v[132:133] op_sel_hi:[1,0]
	v_pk_mul_f32 v[220:221], v[30:31], v[132:133] op_sel_hi:[1,0]
	v_pk_mul_f32 v[222:223], v[24:25], v[132:133] op_sel_hi:[1,0]
	v_pk_mul_f32 v[224:225], v[26:27], v[132:133] op_sel_hi:[1,0]
	v_pk_mul_f32 v[226:227], v[20:21], v[132:133] op_sel_hi:[1,0]
	v_pk_mul_f32 v[228:229], v[22:23], v[132:133] op_sel_hi:[1,0]
	v_pk_mul_f32 v[230:231], v[16:17], v[132:133] op_sel_hi:[1,0]
	v_pk_mul_f32 v[232:233], v[18:19], v[132:133] op_sel_hi:[1,0]
	v_exp_f32_e32 v218, v218
	v_exp_f32_e32 v219, v219
	v_exp_f32_e32 v220, v220
	v_exp_f32_e32 v221, v221
	v_exp_f32_e32 v222, v222
	v_exp_f32_e32 v223, v223
	v_exp_f32_e32 v224, v224
	v_exp_f32_e32 v225, v225
	v_exp_f32_e32 v226, v226
	v_exp_f32_e32 v227, v227
	v_exp_f32_e32 v228, v228
	v_exp_f32_e32 v229, v229
	v_exp_f32_e32 v230, v230
	v_exp_f32_e32 v231, v231
	v_exp_f32_e32 v232, v232
	v_exp_f32_e32 v233, v233
	v_pk_add_f32 v[218:219], v[218:219], v[128:129]
	v_pk_add_f32 v[220:221], v[220:221], v[128:129]
	v_pk_add_f32 v[222:223], v[222:223], v[128:129]
	v_pk_add_f32 v[224:225], v[224:225], v[128:129]
	v_pk_add_f32 v[226:227], v[226:227], v[128:129]
	v_pk_add_f32 v[228:229], v[228:229], v[128:129]
	v_pk_add_f32 v[230:231], v[230:231], v[128:129]
	v_pk_add_f32 v[232:233], v[232:233], v[128:129]
	v_rcp_f32_e32 v218, v218
	v_rcp_f32_e32 v219, v219
	v_rcp_f32_e32 v220, v220
	v_rcp_f32_e32 v221, v221
	v_rcp_f32_e32 v222, v222
	v_rcp_f32_e32 v223, v223
	v_rcp_f32_e32 v224, v224
	v_rcp_f32_e32 v225, v225
	v_rcp_f32_e32 v226, v226
	v_rcp_f32_e32 v227, v227
	v_rcp_f32_e32 v228, v228
	v_rcp_f32_e32 v229, v229
	v_rcp_f32_e32 v230, v230
	v_rcp_f32_e32 v231, v231
	v_rcp_f32_e32 v232, v232
	v_rcp_f32_e32 v233, v233
	v_pk_mul_f32 v[28:29], v[28:29], v[218:219]
	v_pk_mul_f32 v[30:31], v[30:31], v[220:221]
	v_pk_mul_f32 v[24:25], v[24:25], v[222:223]
	v_pk_mul_f32 v[26:27], v[26:27], v[224:225]
	v_pk_mul_f32 v[20:21], v[20:21], v[226:227]
	v_pk_mul_f32 v[22:23], v[22:23], v[228:229]
	v_pk_mul_f32 v[16:17], v[16:17], v[230:231]
	v_pk_mul_f32 v[18:19], v[18:19], v[232:233]
	v_cvt_pk_bf16_f32 v28, v28, v29
	v_cvt_pk_bf16_f32 v29, v30, v31
	v_cvt_pk_bf16_f32 v30, v24, v25
	v_cvt_pk_bf16_f32 v31, v26, v27
	v_cvt_pk_bf16_f32 v20, v20, v21
	v_cvt_pk_bf16_f32 v21, v22, v23
	v_cvt_pk_bf16_f32 v22, v16, v17
	v_cvt_pk_bf16_f32 v23, v18, v19
	v_add_u32_e32 v140, 0xdc000, v139
	global_store_dwordx4 v140, v[28:31], s[8:9]
	v_add_u32_e32 v141, 0xdc100, v139
	global_store_dwordx4 v141, v[20:23], s[8:9]
	v_pk_mul_f32 v[12:13], v[12:13], v[216:217] op_sel_hi:[1,0]
	v_pk_mul_f32 v[14:15], v[14:15], v[216:217] op_sel_hi:[1,0]
	v_pk_mul_f32 v[8:9], v[8:9], v[216:217] op_sel_hi:[1,0]
	v_pk_mul_f32 v[10:11], v[10:11], v[216:217] op_sel_hi:[1,0]
	v_pk_mul_f32 v[4:5], v[4:5], v[216:217] op_sel_hi:[1,0]
	v_pk_mul_f32 v[6:7], v[6:7], v[216:217] op_sel_hi:[1,0]
	v_pk_mul_f32 v[0:1], v[0:1], v[216:217] op_sel_hi:[1,0]
	v_pk_mul_f32 v[2:3], v[2:3], v[216:217] op_sel_hi:[1,0]
	v_pk_mul_f32 v[218:219], v[12:13], v[132:133] op_sel_hi:[1,0]
	v_pk_mul_f32 v[220:221], v[14:15], v[132:133] op_sel_hi:[1,0]
	v_pk_mul_f32 v[222:223], v[8:9], v[132:133] op_sel_hi:[1,0]
	v_pk_mul_f32 v[224:225], v[10:11], v[132:133] op_sel_hi:[1,0]
	v_pk_mul_f32 v[226:227], v[4:5], v[132:133] op_sel_hi:[1,0]
	v_pk_mul_f32 v[228:229], v[6:7], v[132:133] op_sel_hi:[1,0]
	v_pk_mul_f32 v[230:231], v[0:1], v[132:133] op_sel_hi:[1,0]
	v_pk_mul_f32 v[232:233], v[2:3], v[132:133] op_sel_hi:[1,0]
	v_exp_f32_e32 v218, v218
	v_exp_f32_e32 v219, v219
	v_exp_f32_e32 v220, v220
	v_exp_f32_e32 v221, v221
	v_exp_f32_e32 v222, v222
	v_exp_f32_e32 v223, v223
	v_exp_f32_e32 v224, v224
	v_exp_f32_e32 v225, v225
	v_exp_f32_e32 v226, v226
	v_exp_f32_e32 v227, v227
	v_exp_f32_e32 v228, v228
	v_exp_f32_e32 v229, v229
	v_exp_f32_e32 v230, v230
	v_exp_f32_e32 v231, v231
	v_exp_f32_e32 v232, v232
	v_exp_f32_e32 v233, v233
; __device__ __forceinline__ unsigned pk2(float lo, float hi) { return pg8::cvt_pk_bf16(lo, hi); }
; __device__ __forceinline__ float geluf_(float x) { const float z = 1.5957691216057308f * (x + 0.044715f * x * x * x); return x * sigmoidf_(z); }
; __device__ __forceinline__ float sigmoidf_(float x) { return __builtin_amdgcn_rcpf(1.0f + __expf(-x)); }
; __device__ __forceinline__ float siluf_(float x) { return x * sigmoidf_(x); }
;     __device__ __forceinline__ void operator()(const f32x4 (&acc)[2][2][4][2], const pg8::Unit& u, int wr, int wc, int fr, int fq) const {
;     ...
;             const int act = (pn == 7 || pn == 8) ? 1 : (pn == 10 ? 2 : 0);
; #pragma unroll
;             for (int ai = 0; ai < 2; ++ai)
; #pragma unroll
;                 for (int m = 0; m < 4; ++m) {
;                     const int row = row0 + ai * 128 + m * 16; const float r = rs[ai * 4 + m];
; #pragma unroll
;                     for (int bj = 0; bj < 2; ++bj) {
;                         float v[8];
; #pragma unroll
;                         for (int n = 0; n < 2; ++n)
; #pragma unroll
;                             for (int j = 0; j < 4; ++j) { float t = acc[ai][bj][m][n][j] * r; if (act == 1) t = siluf_(t); else if (act == 2) t = geluf_(t); v[n * 4 + j] = t; }
;                         u32x4 w; w.x = pk2(v[0], v[1]); w.y = pk2(v[2], v[3]); w.z = pk2(v[4], v[5]); w.w = pk2(v[6], v[7]);
;                         *(u32x4*)(Z + (size_t)row * IW + pn * 256 + bj * 128 + wc * 32 + 8 * fq) = w;
;                     }
;                 }
	v_pk_add_f32 v[218:219], v[218:219], v[128:129]
	v_pk_add_f32 v[220:221], v[220:221], v[128:129]
	v_pk_add_f32 v[222:223], v[222:223], v[128:129]
	v_pk_add_f32 v[224:225], v[224:225], v[128:129]
	v_pk_add_f32 v[226:227], v[226:227], v[128:129]
	v_pk_add_f32 v[228:229], v[228:229], v[128:129]
	v_pk_add_f32 v[230:231], v[230:231], v[128:129]
	v_pk_add_f32 v[232:233], v[232:233], v[128:129]
	v_rcp_f32_e32 v218, v218
	v_rcp_f32_e32 v219, v219
	v_rcp_f32_e32 v220, v220
	v_rcp_f32_e32 v221, v221
	v_rcp_f32_e32 v222, v222
	v_rcp_f32_e32 v223, v223
	v_rcp_f32_e32 v224, v224
	v_rcp_f32_e32 v225, v225
	v_rcp_f32_e32 v226, v226
	v_rcp_f32_e32 v227, v227
	v_rcp_f32_e32 v228, v228
	v_rcp_f32_e32 v229, v229
	v_rcp_f32_e32 v230, v230
	v_rcp_f32_e32 v231, v231
	v_rcp_f32_e32 v232, v232
	v_rcp_f32_e32 v233, v233
	v_pk_mul_f32 v[12:13], v[12:13], v[218:219]
	v_pk_mul_f32 v[14:15], v[14:15], v[220:221]
	v_pk_mul_f32 v[8:9], v[8:9], v[222:223]
	v_pk_mul_f32 v[10:11], v[10:11], v[224:225]
	v_pk_mul_f32 v[4:5], v[4:5], v[226:227]
	v_pk_mul_f32 v[6:7], v[6:7], v[228:229]
	v_pk_mul_f32 v[0:1], v[0:1], v[230:231]
	v_pk_mul_f32 v[2:3], v[2:3], v[232:233]
	v_cvt_pk_bf16_f32 v12, v12, v13
	v_cvt_pk_bf16_f32 v13, v14, v15
	v_cvt_pk_bf16_f32 v14, v8, v9
	v_cvt_pk_bf16_f32 v15, v10, v11
	v_cvt_pk_bf16_f32 v4, v4, v5
	v_cvt_pk_bf16_f32 v5, v6, v7
	v_cvt_pk_bf16_f32 v6, v0, v1
	v_cvt_pk_bf16_f32 v7, v2, v3
	v_add_u32_e32 v140, 0xf2000, v139
	global_store_dwordx4 v140, v[12:15], s[8:9]
	v_add_u32_e32 v141, 0xf2100, v139
	global_store_dwordx4 v141, v[4:7], s[8:9]
	s_branch .LBB0_1021
.Lwin_act_gelu:
	v_pk_mul_f32 v[124:125], v[124:125], v[202:203] op_sel_hi:[1,0]
	v_pk_mul_f32 v[126:127], v[126:127], v[202:203] op_sel_hi:[1,0]
	v_pk_mul_f32 v[120:121], v[120:121], v[202:203] op_sel_hi:[1,0]
	v_pk_mul_f32 v[122:123], v[122:123], v[202:203] op_sel_hi:[1,0]
	v_pk_mul_f32 v[116:117], v[116:117], v[202:203] op_sel_hi:[1,0]
	v_pk_mul_f32 v[118:119], v[118:119], v[202:203] op_sel_hi:[1,0]
	v_pk_mul_f32 v[112:113], v[112:113], v[202:203] op_sel_hi:[1,0]
	v_pk_mul_f32 v[114:115], v[114:115], v[202:203] op_sel_hi:[1,0]
	v_pk_mul_f32 v[218:219], v[124:125], v[134:135] op_sel_hi:[1,0]
	v_pk_mul_f32 v[220:221], v[126:127], v[134:135] op_sel_hi:[1,0]
	v_pk_mul_f32 v[222:223], v[120:121], v[134:135] op_sel_hi:[1,0]
	v_pk_mul_f32 v[224:225], v[122:123], v[134:135] op_sel_hi:[1,0]
	v_pk_mul_f32 v[226:227], v[116:117], v[134:135] op_sel_hi:[1,0]
	v_pk_mul_f32 v[228:229], v[118:119], v[134:135] op_sel_hi:[1,0]
	v_pk_mul_f32 v[230:231], v[112:113], v[134:135] op_sel_hi:[1,0]
	v_pk_mul_f32 v[232:233], v[114:115], v[134:135] op_sel_hi:[1,0]
	v_pk_mul_f32 v[218:219], v[124:125], v[218:219]
	v_pk_mul_f32 v[220:221], v[126:127], v[220:221]
	v_pk_mul_f32 v[222:223], v[120:121], v[222:223]
	v_pk_mul_f32 v[224:225], v[122:123], v[224:225]
	v_pk_mul_f32 v[226:227], v[116:117], v[226:227]
	v_pk_mul_f32 v[228:229], v[118:119], v[228:229]
	v_pk_mul_f32 v[230:231], v[112:113], v[230:231]
	v_pk_mul_f32 v[232:233], v[114:115], v[232:233]
	v_pk_fma_f32 v[218:219], v[124:125], v[218:219], v[124:125]
	v_pk_fma_f32 v[220:221], v[126:127], v[220:221], v[126:127]
	v_pk_fma_f32 v[222:223], v[120:121], v[222:223], v[120:121]
	v_pk_fma_f32 v[224:225], v[122:123], v[224:225], v[122:123]
	v_pk_fma_f32 v[226:227], v[116:117], v[226:227], v[116:117]
	v_pk_fma_f32 v[228:229], v[118:119], v[228:229], v[118:119]
	v_pk_fma_f32 v[230:231], v[112:113], v[230:231], v[112:113]
	v_pk_fma_f32 v[232:233], v[114:115], v[232:233], v[114:115]
	v_pk_mul_f32 v[218:219], v[218:219], v[136:137] op_sel_hi:[1,0]
	v_pk_mul_f32 v[220:221], v[220:221], v[136:137] op_sel_hi:[1,0]
	v_pk_mul_f32 v[222:223], v[222:223], v[136:137] op_sel_hi:[1,0]
	v_pk_mul_f32 v[224:225], v[224:225], v[136:137] op_sel_hi:[1,0]
	v_pk_mul_f32 v[226:227], v[226:227], v[136:137] op_sel_hi:[1,0]
	v_pk_mul_f32 v[228:229], v[228:229], v[136:137] op_sel_hi:[1,0]
	v_pk_mul_f32 v[230:231], v[230:231], v[136:137] op_sel_hi:[1,0]
	v_pk_mul_f32 v[232:233], v[232:233], v[136:137] op_sel_hi:[1,0]
	v_pk_mul_f32 v[218:219], v[218:219], v[132:133] op_sel_hi:[1,0]
	v_pk_mul_f32 v[220:221], v[220:221], v[132:133] op_sel_hi:[1,0]
	v_pk_mul_f32 v[222:223], v[222:223], v[132:133] op_sel_hi:[1,0]
	v_pk_mul_f32 v[224:225], v[224:225], v[132:133] op_sel_hi:[1,0]
	v_pk_mul_f32 v[226:227], v[226:227], v[132:133] op_sel_hi:[1,0]
	v_pk_mul_f32 v[228:229], v[228:229], v[132:133] op_sel_hi:[1,0]
	v_pk_mul_f32 v[230:231], v[230:231], v[132:133] op_sel_hi:[1,0]
	v_pk_mul_f32 v[232:233], v[232:233], v[132:133] op_sel_hi:[1,0]
	v_exp_f32_e32 v218, v218
	v_exp_f32_e32 v219, v219
	v_exp_f32_e32 v220, v220
	v_exp_f32_e32 v221, v221
	v_exp_f32_e32 v222, v222
	v_exp_f32_e32 v223, v223
	v_exp_f32_e32 v224, v224
	v_exp_f32_e32 v225, v225
	v_exp_f32_e32 v226, v226
	v_exp_f32_e32 v227, v227
	v_exp_f32_e32 v228, v228
	v_exp_f32_e32 v229, v229
	v_exp_f32_e32 v230, v230
	v_exp_f32_e32 v231, v231
	v_exp_f32_e32 v232, v232
	v_exp_f32_e32 v233, v233
	v_pk_add_f32 v[218:219], v[218:219], v[128:129]
	v_pk_add_f32 v[220:221], v[220:221], v[128:129]
	v_pk_add_f32 v[222:223], v[222:223], v[128:129]
	v_pk_add_f32 v[224:225], v[224:225], v[128:129]
	v_pk_add_f32 v[226:227], v[226:227], v[128:129]
	v_pk_add_f32 v[228:229], v[228:229], v[128:129]
	v_pk_add_f32 v[230:231], v[230:231], v[128:129]
	v_pk_add_f32 v[232:233], v[232:233], v[128:129]
	v_rcp_f32_e32 v218, v218
	v_rcp_f32_e32 v219, v219
	v_rcp_f32_e32 v220, v220
	v_rcp_f32_e32 v221, v221
	v_rcp_f32_e32 v222, v222
	v_rcp_f32_e32 v223, v223
	v_rcp_f32_e32 v224, v224
	v_rcp_f32_e32 v225, v225
	v_rcp_f32_e32 v226, v226
	v_rcp_f32_e32 v227, v227
	v_rcp_f32_e32 v228, v228
; __device__ __forceinline__ unsigned pk2(float lo, float hi) { return pg8::cvt_pk_bf16(lo, hi); }
; __device__ __forceinline__ float geluf_(float x) { const float z = 1.5957691216057308f * (x + 0.044715f * x * x * x); return x * sigmoidf_(z); }
; __device__ __forceinline__ float sigmoidf_(float x) { return __builtin_amdgcn_rcpf(1.0f + __expf(-x)); }
; __device__ __forceinline__ float siluf_(float x) { return x * sigmoidf_(x); }
;     __device__ __forceinline__ void operator()(const f32x4 (&acc)[2][2][4][2], const pg8::Unit& u, int wr, int wc, int fr, int fq) const {
;     ...
;                     const int row = row0 + ai * 128 + m * 16; const float r = rs[ai * 4 + m];
; #pragma unroll
;                     for (int bj = 0; bj < 2; ++bj) {
;                         float v[8];
; #pragma unroll
;                         for (int n = 0; n < 2; ++n)
; #pragma unroll
;                             for (int j = 0; j < 4; ++j) { float t = acc[ai][bj][m][n][j] * r; if (act == 1) t = siluf_(t); else if (act == 2) t = geluf_(t); v[n * 4 + j] = t; }
;                         u32x4 w; w.x = pk2(v[0], v[1]); w.y = pk2(v[2], v[3]); w.z = pk2(v[4], v[5]); w.w = pk2(v[6], v[7]);
;                         *(u32x4*)(Z + (size_t)row * IW + pn * 256 + bj * 128 + wc * 32 + 8 * fq) = w;
	v_rcp_f32_e32 v229, v229
	v_rcp_f32_e32 v230, v230
	v_rcp_f32_e32 v231, v231
	v_rcp_f32_e32 v232, v232
	v_rcp_f32_e32 v233, v233
	v_pk_mul_f32 v[124:125], v[124:125], v[218:219]
	v_pk_mul_f32 v[126:127], v[126:127], v[220:221]
	v_pk_mul_f32 v[120:121], v[120:121], v[222:223]
	v_pk_mul_f32 v[122:123], v[122:123], v[224:225]
	v_pk_mul_f32 v[116:117], v[116:117], v[226:227]
	v_pk_mul_f32 v[118:119], v[118:119], v[228:229]
	v_pk_mul_f32 v[112:113], v[112:113], v[230:231]
	v_pk_mul_f32 v[114:115], v[114:115], v[232:233]
	v_cvt_pk_bf16_f32 v124, v124, v125
	v_cvt_pk_bf16_f32 v125, v126, v127
	v_cvt_pk_bf16_f32 v126, v120, v121
	v_cvt_pk_bf16_f32 v127, v122, v123
	v_cvt_pk_bf16_f32 v116, v116, v117
	v_cvt_pk_bf16_f32 v117, v118, v119
	v_cvt_pk_bf16_f32 v118, v112, v113
	v_cvt_pk_bf16_f32 v119, v114, v115
	v_mov_b32_e32 v140, v139
	global_store_dwordx4 v140, v[124:127], s[8:9]
	v_add_u32_e32 v141, 0x100, v139
	global_store_dwordx4 v141, v[116:119], s[8:9]
	v_pk_mul_f32 v[108:109], v[108:109], v[204:205] op_sel_hi:[1,0]
	v_pk_mul_f32 v[110:111], v[110:111], v[204:205] op_sel_hi:[1,0]
	v_pk_mul_f32 v[104:105], v[104:105], v[204:205] op_sel_hi:[1,0]
	v_pk_mul_f32 v[106:107], v[106:107], v[204:205] op_sel_hi:[1,0]
	v_pk_mul_f32 v[100:101], v[100:101], v[204:205] op_sel_hi:[1,0]
	v_pk_mul_f32 v[102:103], v[102:103], v[204:205] op_sel_hi:[1,0]
	v_pk_mul_f32 v[96:97], v[96:97], v[204:205] op_sel_hi:[1,0]
	v_pk_mul_f32 v[98:99], v[98:99], v[204:205] op_sel_hi:[1,0]
	v_pk_mul_f32 v[218:219], v[108:109], v[134:135] op_sel_hi:[1,0]
	v_pk_mul_f32 v[220:221], v[110:111], v[134:135] op_sel_hi:[1,0]
	v_pk_mul_f32 v[222:223], v[104:105], v[134:135] op_sel_hi:[1,0]
	v_pk_mul_f32 v[224:225], v[106:107], v[134:135] op_sel_hi:[1,0]
	v_pk_mul_f32 v[226:227], v[100:101], v[134:135] op_sel_hi:[1,0]
	v_pk_mul_f32 v[228:229], v[102:103], v[134:135] op_sel_hi:[1,0]
	v_pk_mul_f32 v[230:231], v[96:97], v[134:135] op_sel_hi:[1,0]
	v_pk_mul_f32 v[232:233], v[98:99], v[134:135] op_sel_hi:[1,0]
	v_pk_mul_f32 v[218:219], v[108:109], v[218:219]
	v_pk_mul_f32 v[220:221], v[110:111], v[220:221]
	v_pk_mul_f32 v[222:223], v[104:105], v[222:223]
	v_pk_mul_f32 v[224:225], v[106:107], v[224:225]
	v_pk_mul_f32 v[226:227], v[100:101], v[226:227]
	v_pk_mul_f32 v[228:229], v[102:103], v[228:229]
	v_pk_mul_f32 v[230:231], v[96:97], v[230:231]
	v_pk_mul_f32 v[232:233], v[98:99], v[232:233]
	v_pk_fma_f32 v[218:219], v[108:109], v[218:219], v[108:109]
	v_pk_fma_f32 v[220:221], v[110:111], v[220:221], v[110:111]
	v_pk_fma_f32 v[222:223], v[104:105], v[222:223], v[104:105]
	v_pk_fma_f32 v[224:225], v[106:107], v[224:225], v[106:107]
	v_pk_fma_f32 v[226:227], v[100:101], v[226:227], v[100:101]
	v_pk_fma_f32 v[228:229], v[102:103], v[228:229], v[102:103]
	v_pk_fma_f32 v[230:231], v[96:97], v[230:231], v[96:97]
	v_pk_fma_f32 v[232:233], v[98:99], v[232:233], v[98:99]
	v_pk_mul_f32 v[218:219], v[218:219], v[136:137] op_sel_hi:[1,0]
	v_pk_mul_f32 v[220:221], v[220:221], v[136:137] op_sel_hi:[1,0]
	v_pk_mul_f32 v[222:223], v[222:223], v[136:137] op_sel_hi:[1,0]
	v_pk_mul_f32 v[224:225], v[224:225], v[136:137] op_sel_hi:[1,0]
	v_pk_mul_f32 v[226:227], v[226:227], v[136:137] op_sel_hi:[1,0]
	v_pk_mul_f32 v[228:229], v[228:229], v[136:137] op_sel_hi:[1,0]
	v_pk_mul_f32 v[230:231], v[230:231], v[136:137] op_sel_hi:[1,0]
	v_pk_mul_f32 v[232:233], v[232:233], v[136:137] op_sel_hi:[1,0]
	v_pk_mul_f32 v[218:219], v[218:219], v[132:133] op_sel_hi:[1,0]
	v_pk_mul_f32 v[220:221], v[220:221], v[132:133] op_sel_hi:[1,0]
	v_pk_mul_f32 v[222:223], v[222:223], v[132:133] op_sel_hi:[1,0]
	v_pk_mul_f32 v[224:225], v[224:225], v[132:133] op_sel_hi:[1,0]
	v_pk_mul_f32 v[226:227], v[226:227], v[132:133] op_sel_hi:[1,0]
	v_pk_mul_f32 v[228:229], v[228:229], v[132:133] op_sel_hi:[1,0]
	v_pk_mul_f32 v[230:231], v[230:231], v[132:133] op_sel_hi:[1,0]
	v_pk_mul_f32 v[232:233], v[232:233], v[132:133] op_sel_hi:[1,0]
	v_exp_f32_e32 v218, v218
	v_exp_f32_e32 v219, v219
	v_exp_f32_e32 v220, v220
	v_exp_f32_e32 v221, v221
	v_exp_f32_e32 v222, v222
	v_exp_f32_e32 v223, v223
	v_exp_f32_e32 v224, v224
	v_exp_f32_e32 v225, v225
	v_exp_f32_e32 v226, v226
	v_exp_f32_e32 v227, v227
	v_exp_f32_e32 v228, v228
	v_exp_f32_e32 v229, v229
	v_exp_f32_e32 v230, v230
	v_exp_f32_e32 v231, v231
	v_exp_f32_e32 v232, v232
	v_exp_f32_e32 v233, v233
	v_pk_add_f32 v[218:219], v[218:219], v[128:129]
	v_pk_add_f32 v[220:221], v[220:221], v[128:129]
	v_pk_add_f32 v[222:223], v[222:223], v[128:129]
	v_pk_add_f32 v[224:225], v[224:225], v[128:129]
	v_pk_add_f32 v[226:227], v[226:227], v[128:129]
	v_pk_add_f32 v[228:229], v[228:229], v[128:129]
	v_pk_add_f32 v[230:231], v[230:231], v[128:129]
	v_pk_add_f32 v[232:233], v[232:233], v[128:129]
	v_rcp_f32_e32 v218, v218
	v_rcp_f32_e32 v219, v219
	v_rcp_f32_e32 v220, v220
	v_rcp_f32_e32 v221, v221
	v_rcp_f32_e32 v222, v222
	v_rcp_f32_e32 v223, v223
	v_rcp_f32_e32 v224, v224
	v_rcp_f32_e32 v225, v225
	v_rcp_f32_e32 v226, v226
	v_rcp_f32_e32 v227, v227
	v_rcp_f32_e32 v228, v228
	v_rcp_f32_e32 v229, v229
	v_rcp_f32_e32 v230, v230
	v_rcp_f32_e32 v231, v231
	v_rcp_f32_e32 v232, v232
	v_rcp_f32_e32 v233, v233
	v_pk_mul_f32 v[108:109], v[108:109], v[218:219]
	v_pk_mul_f32 v[110:111], v[110:111], v[220:221]
	v_pk_mul_f32 v[104:105], v[104:105], v[222:223]
	v_pk_mul_f32 v[106:107], v[106:107], v[224:225]
	v_pk_mul_f32 v[100:101], v[100:101], v[226:227]
	v_pk_mul_f32 v[102:103], v[102:103], v[228:229]
	v_pk_mul_f32 v[96:97], v[96:97], v[230:231]
	v_pk_mul_f32 v[98:99], v[98:99], v[232:233]
	v_cvt_pk_bf16_f32 v108, v108, v109
	v_cvt_pk_bf16_f32 v109, v110, v111
	v_cvt_pk_bf16_f32 v110, v104, v105
	v_cvt_pk_bf16_f32 v111, v106, v107
; __device__ __forceinline__ unsigned pk2(float lo, float hi) { return pg8::cvt_pk_bf16(lo, hi); }
; __device__ __forceinline__ float geluf_(float x) { const float z = 1.5957691216057308f * (x + 0.044715f * x * x * x); return x * sigmoidf_(z); }
; __device__ __forceinline__ float sigmoidf_(float x) { return __builtin_amdgcn_rcpf(1.0f + __expf(-x)); }
; __device__ __forceinline__ float siluf_(float x) { return x * sigmoidf_(x); }
;     __device__ __forceinline__ void operator()(const f32x4 (&acc)[2][2][4][2], const pg8::Unit& u, int wr, int wc, int fr, int fq) const {
;     ...
;                     const int row = row0 + ai * 128 + m * 16; const float r = rs[ai * 4 + m];
; #pragma unroll
;                     for (int bj = 0; bj < 2; ++bj) {
;                         float v[8];
; #pragma unroll
;                         for (int n = 0; n < 2; ++n)
; #pragma unroll
;                             for (int j = 0; j < 4; ++j) { float t = acc[ai][bj][m][n][j] * r; if (act == 1) t = siluf_(t); else if (act == 2) t = geluf_(t); v[n * 4 + j] = t; }
;                         u32x4 w; w.x = pk2(v[0], v[1]); w.y = pk2(v[2], v[3]); w.z = pk2(v[4], v[5]); w.w = pk2(v[6], v[7]);
;                         *(u32x4*)(Z + (size_t)row * IW + pn * 256 + bj * 128 + wc * 32 + 8 * fq) = w;
	v_cvt_pk_bf16_f32 v100, v100, v101
	v_cvt_pk_bf16_f32 v101, v102, v103
	v_cvt_pk_bf16_f32 v102, v96, v97
	v_cvt_pk_bf16_f32 v103, v98, v99
	v_add_u32_e32 v140, 0x16000, v139
	global_store_dwordx4 v140, v[108:111], s[8:9]
	v_add_u32_e32 v141, 0x16100, v139
	global_store_dwordx4 v141, v[100:103], s[8:9]
	v_pk_mul_f32 v[92:93], v[92:93], v[206:207] op_sel_hi:[1,0]
	v_pk_mul_f32 v[94:95], v[94:95], v[206:207] op_sel_hi:[1,0]
	v_pk_mul_f32 v[88:89], v[88:89], v[206:207] op_sel_hi:[1,0]
	v_pk_mul_f32 v[90:91], v[90:91], v[206:207] op_sel_hi:[1,0]
	v_pk_mul_f32 v[84:85], v[84:85], v[206:207] op_sel_hi:[1,0]
	v_pk_mul_f32 v[86:87], v[86:87], v[206:207] op_sel_hi:[1,0]
	v_pk_mul_f32 v[80:81], v[80:81], v[206:207] op_sel_hi:[1,0]
	v_pk_mul_f32 v[82:83], v[82:83], v[206:207] op_sel_hi:[1,0]
	v_pk_mul_f32 v[218:219], v[92:93], v[134:135] op_sel_hi:[1,0]
	v_pk_mul_f32 v[220:221], v[94:95], v[134:135] op_sel_hi:[1,0]
	v_pk_mul_f32 v[222:223], v[88:89], v[134:135] op_sel_hi:[1,0]
	v_pk_mul_f32 v[224:225], v[90:91], v[134:135] op_sel_hi:[1,0]
	v_pk_mul_f32 v[226:227], v[84:85], v[134:135] op_sel_hi:[1,0]
	v_pk_mul_f32 v[228:229], v[86:87], v[134:135] op_sel_hi:[1,0]
	v_pk_mul_f32 v[230:231], v[80:81], v[134:135] op_sel_hi:[1,0]
	v_pk_mul_f32 v[232:233], v[82:83], v[134:135] op_sel_hi:[1,0]
	v_pk_mul_f32 v[218:219], v[92:93], v[218:219]
	v_pk_mul_f32 v[220:221], v[94:95], v[220:221]
	v_pk_mul_f32 v[222:223], v[88:89], v[222:223]
	v_pk_mul_f32 v[224:225], v[90:91], v[224:225]
	v_pk_mul_f32 v[226:227], v[84:85], v[226:227]
	v_pk_mul_f32 v[228:229], v[86:87], v[228:229]
	v_pk_mul_f32 v[230:231], v[80:81], v[230:231]
	v_pk_mul_f32 v[232:233], v[82:83], v[232:233]
	v_pk_fma_f32 v[218:219], v[92:93], v[218:219], v[92:93]
	v_pk_fma_f32 v[220:221], v[94:95], v[220:221], v[94:95]
	v_pk_fma_f32 v[222:223], v[88:89], v[222:223], v[88:89]
	v_pk_fma_f32 v[224:225], v[90:91], v[224:225], v[90:91]
	v_pk_fma_f32 v[226:227], v[84:85], v[226:227], v[84:85]
	v_pk_fma_f32 v[228:229], v[86:87], v[228:229], v[86:87]
	v_pk_fma_f32 v[230:231], v[80:81], v[230:231], v[80:81]
	v_pk_fma_f32 v[232:233], v[82:83], v[232:233], v[82:83]
	v_pk_mul_f32 v[218:219], v[218:219], v[136:137] op_sel_hi:[1,0]
	v_pk_mul_f32 v[220:221], v[220:221], v[136:137] op_sel_hi:[1,0]
	v_pk_mul_f32 v[222:223], v[222:223], v[136:137] op_sel_hi:[1,0]
	v_pk_mul_f32 v[224:225], v[224:225], v[136:137] op_sel_hi:[1,0]
	v_pk_mul_f32 v[226:227], v[226:227], v[136:137] op_sel_hi:[1,0]
	v_pk_mul_f32 v[228:229], v[228:229], v[136:137] op_sel_hi:[1,0]
	v_pk_mul_f32 v[230:231], v[230:231], v[136:137] op_sel_hi:[1,0]
	v_pk_mul_f32 v[232:233], v[232:233], v[136:137] op_sel_hi:[1,0]
	v_pk_mul_f32 v[218:219], v[218:219], v[132:133] op_sel_hi:[1,0]
	v_pk_mul_f32 v[220:221], v[220:221], v[132:133] op_sel_hi:[1,0]
	v_pk_mul_f32 v[222:223], v[222:223], v[132:133] op_sel_hi:[1,0]
	v_pk_mul_f32 v[224:225], v[224:225], v[132:133] op_sel_hi:[1,0]
	v_pk_mul_f32 v[226:227], v[226:227], v[132:133] op_sel_hi:[1,0]
	v_pk_mul_f32 v[228:229], v[228:229], v[132:133] op_sel_hi:[1,0]
	v_pk_mul_f32 v[230:231], v[230:231], v[132:133] op_sel_hi:[1,0]
	v_pk_mul_f32 v[232:233], v[232:233], v[132:133] op_sel_hi:[1,0]
	v_exp_f32_e32 v218, v218
	v_exp_f32_e32 v219, v219
	v_exp_f32_e32 v220, v220
	v_exp_f32_e32 v221, v221
	v_exp_f32_e32 v222, v222
	v_exp_f32_e32 v223, v223
	v_exp_f32_e32 v224, v224
	v_exp_f32_e32 v225, v225
	v_exp_f32_e32 v226, v226
	v_exp_f32_e32 v227, v227
	v_exp_f32_e32 v228, v228
	v_exp_f32_e32 v229, v229
	v_exp_f32_e32 v230, v230
	v_exp_f32_e32 v231, v231
	v_exp_f32_e32 v232, v232
	v_exp_f32_e32 v233, v233
	v_pk_add_f32 v[218:219], v[218:219], v[128:129]
	v_pk_add_f32 v[220:221], v[220:221], v[128:129]
	v_pk_add_f32 v[222:223], v[222:223], v[128:129]
	v_pk_add_f32 v[224:225], v[224:225], v[128:129]
	v_pk_add_f32 v[226:227], v[226:227], v[128:129]
	v_pk_add_f32 v[228:229], v[228:229], v[128:129]
	v_pk_add_f32 v[230:231], v[230:231], v[128:129]
	v_pk_add_f32 v[232:233], v[232:233], v[128:129]
	v_rcp_f32_e32 v218, v218
	v_rcp_f32_e32 v219, v219
	v_rcp_f32_e32 v220, v220
	v_rcp_f32_e32 v221, v221
	v_rcp_f32_e32 v222, v222
	v_rcp_f32_e32 v223, v223
	v_rcp_f32_e32 v224, v224
	v_rcp_f32_e32 v225, v225
	v_rcp_f32_e32 v226, v226
	v_rcp_f32_e32 v227, v227
	v_rcp_f32_e32 v228, v228
	v_rcp_f32_e32 v229, v229
	v_rcp_f32_e32 v230, v230
	v_rcp_f32_e32 v231, v231
	v_rcp_f32_e32 v232, v232
	v_rcp_f32_e32 v233, v233
	v_pk_mul_f32 v[92:93], v[92:93], v[218:219]
	v_pk_mul_f32 v[94:95], v[94:95], v[220:221]
	v_pk_mul_f32 v[88:89], v[88:89], v[222:223]
	v_pk_mul_f32 v[90:91], v[90:91], v[224:225]
	v_pk_mul_f32 v[84:85], v[84:85], v[226:227]
	v_pk_mul_f32 v[86:87], v[86:87], v[228:229]
	v_pk_mul_f32 v[80:81], v[80:81], v[230:231]
	v_pk_mul_f32 v[82:83], v[82:83], v[232:233]
	v_cvt_pk_bf16_f32 v92, v92, v93
	v_cvt_pk_bf16_f32 v93, v94, v95
	v_cvt_pk_bf16_f32 v94, v88, v89
	v_cvt_pk_bf16_f32 v95, v90, v91
	v_cvt_pk_bf16_f32 v84, v84, v85
	v_cvt_pk_bf16_f32 v85, v86, v87
	v_cvt_pk_bf16_f32 v86, v80, v81
	v_cvt_pk_bf16_f32 v87, v82, v83
	v_add_u32_e32 v140, 0x2c000, v139
	global_store_dwordx4 v140, v[92:95], s[8:9]
	v_add_u32_e32 v141, 0x2c100, v139
	global_store_dwordx4 v141, v[84:87], s[8:9]
	v_pk_mul_f32 v[76:77], v[76:77], v[208:209] op_sel_hi:[1,0]
	v_pk_mul_f32 v[78:79], v[78:79], v[208:209] op_sel_hi:[1,0]
	v_pk_mul_f32 v[72:73], v[72:73], v[208:209] op_sel_hi:[1,0]
	v_pk_mul_f32 v[74:75], v[74:75], v[208:209] op_sel_hi:[1,0]
	v_pk_mul_f32 v[68:69], v[68:69], v[208:209] op_sel_hi:[1,0]
	v_pk_mul_f32 v[70:71], v[70:71], v[208:209] op_sel_hi:[1,0]
	v_pk_mul_f32 v[64:65], v[64:65], v[208:209] op_sel_hi:[1,0]
	v_pk_mul_f32 v[66:67], v[66:67], v[208:209] op_sel_hi:[1,0]
; __device__ __forceinline__ unsigned pk2(float lo, float hi) { return pg8::cvt_pk_bf16(lo, hi); }
; __device__ __forceinline__ float geluf_(float x) { const float z = 1.5957691216057308f * (x + 0.044715f * x * x * x); return x * sigmoidf_(z); }
; __device__ __forceinline__ float sigmoidf_(float x) { return __builtin_amdgcn_rcpf(1.0f + __expf(-x)); }
; __device__ __forceinline__ float siluf_(float x) { return x * sigmoidf_(x); }
;     __device__ __forceinline__ void operator()(const f32x4 (&acc)[2][2][4][2], const pg8::Unit& u, int wr, int wc, int fr, int fq) const {
;     ...
;                     const int row = row0 + ai * 128 + m * 16; const float r = rs[ai * 4 + m];
; #pragma unroll
;                     for (int bj = 0; bj < 2; ++bj) {
;                         float v[8];
; #pragma unroll
;                         for (int n = 0; n < 2; ++n)
; #pragma unroll
;                             for (int j = 0; j < 4; ++j) { float t = acc[ai][bj][m][n][j] * r; if (act == 1) t = siluf_(t); else if (act == 2) t = geluf_(t); v[n * 4 + j] = t; }
;                         u32x4 w; w.x = pk2(v[0], v[1]); w.y = pk2(v[2], v[3]); w.z = pk2(v[4], v[5]); w.w = pk2(v[6], v[7]);
;                         *(u32x4*)(Z + (size_t)row * IW + pn * 256 + bj * 128 + wc * 32 + 8 * fq) = w;
	v_pk_mul_f32 v[218:219], v[76:77], v[134:135] op_sel_hi:[1,0]
	v_pk_mul_f32 v[220:221], v[78:79], v[134:135] op_sel_hi:[1,0]
	v_pk_mul_f32 v[222:223], v[72:73], v[134:135] op_sel_hi:[1,0]
	v_pk_mul_f32 v[224:225], v[74:75], v[134:135] op_sel_hi:[1,0]
	v_pk_mul_f32 v[226:227], v[68:69], v[134:135] op_sel_hi:[1,0]
	v_pk_mul_f32 v[228:229], v[70:71], v[134:135] op_sel_hi:[1,0]
	v_pk_mul_f32 v[230:231], v[64:65], v[134:135] op_sel_hi:[1,0]
	v_pk_mul_f32 v[232:233], v[66:67], v[134:135] op_sel_hi:[1,0]
	v_pk_mul_f32 v[218:219], v[76:77], v[218:219]
	v_pk_mul_f32 v[220:221], v[78:79], v[220:221]
	v_pk_mul_f32 v[222:223], v[72:73], v[222:223]
	v_pk_mul_f32 v[224:225], v[74:75], v[224:225]
	v_pk_mul_f32 v[226:227], v[68:69], v[226:227]
	v_pk_mul_f32 v[228:229], v[70:71], v[228:229]
	v_pk_mul_f32 v[230:231], v[64:65], v[230:231]
	v_pk_mul_f32 v[232:233], v[66:67], v[232:233]
	v_pk_fma_f32 v[218:219], v[76:77], v[218:219], v[76:77]
	v_pk_fma_f32 v[220:221], v[78:79], v[220:221], v[78:79]
	v_pk_fma_f32 v[222:223], v[72:73], v[222:223], v[72:73]
	v_pk_fma_f32 v[224:225], v[74:75], v[224:225], v[74:75]
	v_pk_fma_f32 v[226:227], v[68:69], v[226:227], v[68:69]
	v_pk_fma_f32 v[228:229], v[70:71], v[228:229], v[70:71]
	v_pk_fma_f32 v[230:231], v[64:65], v[230:231], v[64:65]
	v_pk_fma_f32 v[232:233], v[66:67], v[232:233], v[66:67]
	v_pk_mul_f32 v[218:219], v[218:219], v[136:137] op_sel_hi:[1,0]
	v_pk_mul_f32 v[220:221], v[220:221], v[136:137] op_sel_hi:[1,0]
	v_pk_mul_f32 v[222:223], v[222:223], v[136:137] op_sel_hi:[1,0]
	v_pk_mul_f32 v[224:225], v[224:225], v[136:137] op_sel_hi:[1,0]
	v_pk_mul_f32 v[226:227], v[226:227], v[136:137] op_sel_hi:[1,0]
	v_pk_mul_f32 v[228:229], v[228:229], v[136:137] op_sel_hi:[1,0]
	v_pk_mul_f32 v[230:231], v[230:231], v[136:137] op_sel_hi:[1,0]
	v_pk_mul_f32 v[232:233], v[232:233], v[136:137] op_sel_hi:[1,0]
	v_pk_mul_f32 v[218:219], v[218:219], v[132:133] op_sel_hi:[1,0]
	v_pk_mul_f32 v[220:221], v[220:221], v[132:133] op_sel_hi:[1,0]
	v_pk_mul_f32 v[222:223], v[222:223], v[132:133] op_sel_hi:[1,0]
	v_pk_mul_f32 v[224:225], v[224:225], v[132:133] op_sel_hi:[1,0]
	v_pk_mul_f32 v[226:227], v[226:227], v[132:133] op_sel_hi:[1,0]
	v_pk_mul_f32 v[228:229], v[228:229], v[132:133] op_sel_hi:[1,0]
	v_pk_mul_f32 v[230:231], v[230:231], v[132:133] op_sel_hi:[1,0]
	v_pk_mul_f32 v[232:233], v[232:233], v[132:133] op_sel_hi:[1,0]
	v_exp_f32_e32 v218, v218
	v_exp_f32_e32 v219, v219
	v_exp_f32_e32 v220, v220
	v_exp_f32_e32 v221, v221
	v_exp_f32_e32 v222, v222
	v_exp_f32_e32 v223, v223
	v_exp_f32_e32 v224, v224
	v_exp_f32_e32 v225, v225
	v_exp_f32_e32 v226, v226
	v_exp_f32_e32 v227, v227
	v_exp_f32_e32 v228, v228
	v_exp_f32_e32 v229, v229
	v_exp_f32_e32 v230, v230
	v_exp_f32_e32 v231, v231
	v_exp_f32_e32 v232, v232
	v_exp_f32_e32 v233, v233
	v_pk_add_f32 v[218:219], v[218:219], v[128:129]
	v_pk_add_f32 v[220:221], v[220:221], v[128:129]
	v_pk_add_f32 v[222:223], v[222:223], v[128:129]
	v_pk_add_f32 v[224:225], v[224:225], v[128:129]
	v_pk_add_f32 v[226:227], v[226:227], v[128:129]
	v_pk_add_f32 v[228:229], v[228:229], v[128:129]
	v_pk_add_f32 v[230:231], v[230:231], v[128:129]
	v_pk_add_f32 v[232:233], v[232:233], v[128:129]
	v_rcp_f32_e32 v218, v218
	v_rcp_f32_e32 v219, v219
	v_rcp_f32_e32 v220, v220
	v_rcp_f32_e32 v221, v221
	v_rcp_f32_e32 v222, v222
	v_rcp_f32_e32 v223, v223
	v_rcp_f32_e32 v224, v224
	v_rcp_f32_e32 v225, v225
	v_rcp_f32_e32 v226, v226
	v_rcp_f32_e32 v227, v227
	v_rcp_f32_e32 v228, v228
	v_rcp_f32_e32 v229, v229
	v_rcp_f32_e32 v230, v230
	v_rcp_f32_e32 v231, v231
	v_rcp_f32_e32 v232, v232
	v_rcp_f32_e32 v233, v233
	v_pk_mul_f32 v[76:77], v[76:77], v[218:219]
	v_pk_mul_f32 v[78:79], v[78:79], v[220:221]
	v_pk_mul_f32 v[72:73], v[72:73], v[222:223]
	v_pk_mul_f32 v[74:75], v[74:75], v[224:225]
	v_pk_mul_f32 v[68:69], v[68:69], v[226:227]
	v_pk_mul_f32 v[70:71], v[70:71], v[228:229]
	v_pk_mul_f32 v[64:65], v[64:65], v[230:231]
	v_pk_mul_f32 v[66:67], v[66:67], v[232:233]
	v_cvt_pk_bf16_f32 v76, v76, v77
	v_cvt_pk_bf16_f32 v77, v78, v79
	v_cvt_pk_bf16_f32 v78, v72, v73
	v_cvt_pk_bf16_f32 v79, v74, v75
	v_cvt_pk_bf16_f32 v68, v68, v69
	v_cvt_pk_bf16_f32 v69, v70, v71
	v_cvt_pk_bf16_f32 v70, v64, v65
	v_cvt_pk_bf16_f32 v71, v66, v67
	v_add_u32_e32 v140, 0x42000, v139
	global_store_dwordx4 v140, v[76:79], s[8:9]
	v_add_u32_e32 v141, 0x42100, v139
	global_store_dwordx4 v141, v[68:71], s[8:9]
	v_pk_mul_f32 v[60:61], v[60:61], v[210:211] op_sel_hi:[1,0]
	v_pk_mul_f32 v[62:63], v[62:63], v[210:211] op_sel_hi:[1,0]
	v_pk_mul_f32 v[56:57], v[56:57], v[210:211] op_sel_hi:[1,0]
	v_pk_mul_f32 v[58:59], v[58:59], v[210:211] op_sel_hi:[1,0]
	v_pk_mul_f32 v[52:53], v[52:53], v[210:211] op_sel_hi:[1,0]
	v_pk_mul_f32 v[54:55], v[54:55], v[210:211] op_sel_hi:[1,0]
	v_pk_mul_f32 v[48:49], v[48:49], v[210:211] op_sel_hi:[1,0]
	v_pk_mul_f32 v[50:51], v[50:51], v[210:211] op_sel_hi:[1,0]
	v_pk_mul_f32 v[218:219], v[60:61], v[134:135] op_sel_hi:[1,0]
	v_pk_mul_f32 v[220:221], v[62:63], v[134:135] op_sel_hi:[1,0]
	v_pk_mul_f32 v[222:223], v[56:57], v[134:135] op_sel_hi:[1,0]
	v_pk_mul_f32 v[224:225], v[58:59], v[134:135] op_sel_hi:[1,0]
	v_pk_mul_f32 v[226:227], v[52:53], v[134:135] op_sel_hi:[1,0]
	v_pk_mul_f32 v[228:229], v[54:55], v[134:135] op_sel_hi:[1,0]
	v_pk_mul_f32 v[230:231], v[48:49], v[134:135] op_sel_hi:[1,0]
	v_pk_mul_f32 v[232:233], v[50:51], v[134:135] op_sel_hi:[1,0]
	v_pk_mul_f32 v[218:219], v[60:61], v[218:219]
	v_pk_mul_f32 v[220:221], v[62:63], v[220:221]
	v_pk_mul_f32 v[222:223], v[56:57], v[222:223]
	v_pk_mul_f32 v[224:225], v[58:59], v[224:225]
	v_pk_mul_f32 v[226:227], v[52:53], v[226:227]
	v_pk_mul_f32 v[228:229], v[54:55], v[228:229]
; __device__ __forceinline__ unsigned pk2(float lo, float hi) { return pg8::cvt_pk_bf16(lo, hi); }
; __device__ __forceinline__ float geluf_(float x) { const float z = 1.5957691216057308f * (x + 0.044715f * x * x * x); return x * sigmoidf_(z); }
; __device__ __forceinline__ float sigmoidf_(float x) { return __builtin_amdgcn_rcpf(1.0f + __expf(-x)); }
; __device__ __forceinline__ float siluf_(float x) { return x * sigmoidf_(x); }
;     __device__ __forceinline__ void operator()(const f32x4 (&acc)[2][2][4][2], const pg8::Unit& u, int wr, int wc, int fr, int fq) const {
;     ...
;                     const int row = row0 + ai * 128 + m * 16; const float r = rs[ai * 4 + m];
; #pragma unroll
;                     for (int bj = 0; bj < 2; ++bj) {
;                         float v[8];
; #pragma unroll
;                         for (int n = 0; n < 2; ++n)
; #pragma unroll
;                             for (int j = 0; j < 4; ++j) { float t = acc[ai][bj][m][n][j] * r; if (act == 1) t = siluf_(t); else if (act == 2) t = geluf_(t); v[n * 4 + j] = t; }
;                         u32x4 w; w.x = pk2(v[0], v[1]); w.y = pk2(v[2], v[3]); w.z = pk2(v[4], v[5]); w.w = pk2(v[6], v[7]);
;                         *(u32x4*)(Z + (size_t)row * IW + pn * 256 + bj * 128 + wc * 32 + 8 * fq) = w;
	v_pk_mul_f32 v[230:231], v[48:49], v[230:231]
	v_pk_mul_f32 v[232:233], v[50:51], v[232:233]
	v_pk_fma_f32 v[218:219], v[60:61], v[218:219], v[60:61]
	v_pk_fma_f32 v[220:221], v[62:63], v[220:221], v[62:63]
	v_pk_fma_f32 v[222:223], v[56:57], v[222:223], v[56:57]
	v_pk_fma_f32 v[224:225], v[58:59], v[224:225], v[58:59]
	v_pk_fma_f32 v[226:227], v[52:53], v[226:227], v[52:53]
	v_pk_fma_f32 v[228:229], v[54:55], v[228:229], v[54:55]
	v_pk_fma_f32 v[230:231], v[48:49], v[230:231], v[48:49]
	v_pk_fma_f32 v[232:233], v[50:51], v[232:233], v[50:51]
	v_pk_mul_f32 v[218:219], v[218:219], v[136:137] op_sel_hi:[1,0]
	v_pk_mul_f32 v[220:221], v[220:221], v[136:137] op_sel_hi:[1,0]
	v_pk_mul_f32 v[222:223], v[222:223], v[136:137] op_sel_hi:[1,0]
	v_pk_mul_f32 v[224:225], v[224:225], v[136:137] op_sel_hi:[1,0]
	v_pk_mul_f32 v[226:227], v[226:227], v[136:137] op_sel_hi:[1,0]
	v_pk_mul_f32 v[228:229], v[228:229], v[136:137] op_sel_hi:[1,0]
	v_pk_mul_f32 v[230:231], v[230:231], v[136:137] op_sel_hi:[1,0]
	v_pk_mul_f32 v[232:233], v[232:233], v[136:137] op_sel_hi:[1,0]
	v_pk_mul_f32 v[218:219], v[218:219], v[132:133] op_sel_hi:[1,0]
	v_pk_mul_f32 v[220:221], v[220:221], v[132:133] op_sel_hi:[1,0]
	v_pk_mul_f32 v[222:223], v[222:223], v[132:133] op_sel_hi:[1,0]
	v_pk_mul_f32 v[224:225], v[224:225], v[132:133] op_sel_hi:[1,0]
	v_pk_mul_f32 v[226:227], v[226:227], v[132:133] op_sel_hi:[1,0]
	v_pk_mul_f32 v[228:229], v[228:229], v[132:133] op_sel_hi:[1,0]
	v_pk_mul_f32 v[230:231], v[230:231], v[132:133] op_sel_hi:[1,0]
	v_pk_mul_f32 v[232:233], v[232:233], v[132:133] op_sel_hi:[1,0]
	v_exp_f32_e32 v218, v218
	v_exp_f32_e32 v219, v219
	v_exp_f32_e32 v220, v220
	v_exp_f32_e32 v221, v221
	v_exp_f32_e32 v222, v222
	v_exp_f32_e32 v223, v223
	v_exp_f32_e32 v224, v224
	v_exp_f32_e32 v225, v225
	v_exp_f32_e32 v226, v226
	v_exp_f32_e32 v227, v227
	v_exp_f32_e32 v228, v228
	v_exp_f32_e32 v229, v229
	v_exp_f32_e32 v230, v230
	v_exp_f32_e32 v231, v231
	v_exp_f32_e32 v232, v232
	v_exp_f32_e32 v233, v233
	v_pk_add_f32 v[218:219], v[218:219], v[128:129]
	v_pk_add_f32 v[220:221], v[220:221], v[128:129]
	v_pk_add_f32 v[222:223], v[222:223], v[128:129]
	v_pk_add_f32 v[224:225], v[224:225], v[128:129]
	v_pk_add_f32 v[226:227], v[226:227], v[128:129]
	v_pk_add_f32 v[228:229], v[228:229], v[128:129]
	v_pk_add_f32 v[230:231], v[230:231], v[128:129]
	v_pk_add_f32 v[232:233], v[232:233], v[128:129]
	v_rcp_f32_e32 v218, v218
	v_rcp_f32_e32 v219, v219
	v_rcp_f32_e32 v220, v220
	v_rcp_f32_e32 v221, v221
	v_rcp_f32_e32 v222, v222
	v_rcp_f32_e32 v223, v223
	v_rcp_f32_e32 v224, v224
	v_rcp_f32_e32 v225, v225
	v_rcp_f32_e32 v226, v226
	v_rcp_f32_e32 v227, v227
	v_rcp_f32_e32 v228, v228
	v_rcp_f32_e32 v229, v229
	v_rcp_f32_e32 v230, v230
	v_rcp_f32_e32 v231, v231
	v_rcp_f32_e32 v232, v232
	v_rcp_f32_e32 v233, v233
	v_pk_mul_f32 v[60:61], v[60:61], v[218:219]
	v_pk_mul_f32 v[62:63], v[62:63], v[220:221]
	v_pk_mul_f32 v[56:57], v[56:57], v[222:223]
	v_pk_mul_f32 v[58:59], v[58:59], v[224:225]
	v_pk_mul_f32 v[52:53], v[52:53], v[226:227]
	v_pk_mul_f32 v[54:55], v[54:55], v[228:229]
	v_pk_mul_f32 v[48:49], v[48:49], v[230:231]
	v_pk_mul_f32 v[50:51], v[50:51], v[232:233]
	v_cvt_pk_bf16_f32 v60, v60, v61
	v_cvt_pk_bf16_f32 v61, v62, v63
	v_cvt_pk_bf16_f32 v62, v56, v57
	v_cvt_pk_bf16_f32 v63, v58, v59
	v_cvt_pk_bf16_f32 v52, v52, v53
	v_cvt_pk_bf16_f32 v53, v54, v55
	v_cvt_pk_bf16_f32 v54, v48, v49
	v_cvt_pk_bf16_f32 v55, v50, v51
	v_add_u32_e32 v140, 0xb0000, v139
	global_store_dwordx4 v140, v[60:63], s[8:9]
	v_add_u32_e32 v141, 0xb0100, v139
	global_store_dwordx4 v141, v[52:55], s[8:9]
	v_pk_mul_f32 v[44:45], v[44:45], v[212:213] op_sel_hi:[1,0]
	v_pk_mul_f32 v[46:47], v[46:47], v[212:213] op_sel_hi:[1,0]
	v_pk_mul_f32 v[40:41], v[40:41], v[212:213] op_sel_hi:[1,0]
	v_pk_mul_f32 v[42:43], v[42:43], v[212:213] op_sel_hi:[1,0]
	v_pk_mul_f32 v[36:37], v[36:37], v[212:213] op_sel_hi:[1,0]
	v_pk_mul_f32 v[38:39], v[38:39], v[212:213] op_sel_hi:[1,0]
	v_pk_mul_f32 v[32:33], v[32:33], v[212:213] op_sel_hi:[1,0]
	v_pk_mul_f32 v[34:35], v[34:35], v[212:213] op_sel_hi:[1,0]
	v_pk_mul_f32 v[218:219], v[44:45], v[134:135] op_sel_hi:[1,0]
	v_pk_mul_f32 v[220:221], v[46:47], v[134:135] op_sel_hi:[1,0]
	v_pk_mul_f32 v[222:223], v[40:41], v[134:135] op_sel_hi:[1,0]
	v_pk_mul_f32 v[224:225], v[42:43], v[134:135] op_sel_hi:[1,0]
	v_pk_mul_f32 v[226:227], v[36:37], v[134:135] op_sel_hi:[1,0]
	v_pk_mul_f32 v[228:229], v[38:39], v[134:135] op_sel_hi:[1,0]
	v_pk_mul_f32 v[230:231], v[32:33], v[134:135] op_sel_hi:[1,0]
	v_pk_mul_f32 v[232:233], v[34:35], v[134:135] op_sel_hi:[1,0]
	v_pk_mul_f32 v[218:219], v[44:45], v[218:219]
	v_pk_mul_f32 v[220:221], v[46:47], v[220:221]
	v_pk_mul_f32 v[222:223], v[40:41], v[222:223]
	v_pk_mul_f32 v[224:225], v[42:43], v[224:225]
	v_pk_mul_f32 v[226:227], v[36:37], v[226:227]
	v_pk_mul_f32 v[228:229], v[38:39], v[228:229]
	v_pk_mul_f32 v[230:231], v[32:33], v[230:231]
	v_pk_mul_f32 v[232:233], v[34:35], v[232:233]
	v_pk_fma_f32 v[218:219], v[44:45], v[218:219], v[44:45]
	v_pk_fma_f32 v[220:221], v[46:47], v[220:221], v[46:47]
	v_pk_fma_f32 v[222:223], v[40:41], v[222:223], v[40:41]
	v_pk_fma_f32 v[224:225], v[42:43], v[224:225], v[42:43]
	v_pk_fma_f32 v[226:227], v[36:37], v[226:227], v[36:37]
	v_pk_fma_f32 v[228:229], v[38:39], v[228:229], v[38:39]
	v_pk_fma_f32 v[230:231], v[32:33], v[230:231], v[32:33]
	v_pk_fma_f32 v[232:233], v[34:35], v[232:233], v[34:35]
	v_pk_mul_f32 v[218:219], v[218:219], v[136:137] op_sel_hi:[1,0]
	v_pk_mul_f32 v[220:221], v[220:221], v[136:137] op_sel_hi:[1,0]
	v_pk_mul_f32 v[222:223], v[222:223], v[136:137] op_sel_hi:[1,0]
; __device__ __forceinline__ unsigned pk2(float lo, float hi) { return pg8::cvt_pk_bf16(lo, hi); }
; __device__ __forceinline__ float geluf_(float x) { const float z = 1.5957691216057308f * (x + 0.044715f * x * x * x); return x * sigmoidf_(z); }
; __device__ __forceinline__ float sigmoidf_(float x) { return __builtin_amdgcn_rcpf(1.0f + __expf(-x)); }
; __device__ __forceinline__ float siluf_(float x) { return x * sigmoidf_(x); }
;     __device__ __forceinline__ void operator()(const f32x4 (&acc)[2][2][4][2], const pg8::Unit& u, int wr, int wc, int fr, int fq) const {
;     ...
;                     const int row = row0 + ai * 128 + m * 16; const float r = rs[ai * 4 + m];
; #pragma unroll
;                     for (int bj = 0; bj < 2; ++bj) {
;                         float v[8];
; #pragma unroll
;                         for (int n = 0; n < 2; ++n)
; #pragma unroll
;                             for (int j = 0; j < 4; ++j) { float t = acc[ai][bj][m][n][j] * r; if (act == 1) t = siluf_(t); else if (act == 2) t = geluf_(t); v[n * 4 + j] = t; }
;                         u32x4 w; w.x = pk2(v[0], v[1]); w.y = pk2(v[2], v[3]); w.z = pk2(v[4], v[5]); w.w = pk2(v[6], v[7]);
;                         *(u32x4*)(Z + (size_t)row * IW + pn * 256 + bj * 128 + wc * 32 + 8 * fq) = w;
	v_pk_mul_f32 v[224:225], v[224:225], v[136:137] op_sel_hi:[1,0]
	v_pk_mul_f32 v[226:227], v[226:227], v[136:137] op_sel_hi:[1,0]
	v_pk_mul_f32 v[228:229], v[228:229], v[136:137] op_sel_hi:[1,0]
	v_pk_mul_f32 v[230:231], v[230:231], v[136:137] op_sel_hi:[1,0]
	v_pk_mul_f32 v[232:233], v[232:233], v[136:137] op_sel_hi:[1,0]
	v_pk_mul_f32 v[218:219], v[218:219], v[132:133] op_sel_hi:[1,0]
	v_pk_mul_f32 v[220:221], v[220:221], v[132:133] op_sel_hi:[1,0]
	v_pk_mul_f32 v[222:223], v[222:223], v[132:133] op_sel_hi:[1,0]
	v_pk_mul_f32 v[224:225], v[224:225], v[132:133] op_sel_hi:[1,0]
	v_pk_mul_f32 v[226:227], v[226:227], v[132:133] op_sel_hi:[1,0]
	v_pk_mul_f32 v[228:229], v[228:229], v[132:133] op_sel_hi:[1,0]
	v_pk_mul_f32 v[230:231], v[230:231], v[132:133] op_sel_hi:[1,0]
	v_pk_mul_f32 v[232:233], v[232:233], v[132:133] op_sel_hi:[1,0]
	v_exp_f32_e32 v218, v218
	v_exp_f32_e32 v219, v219
	v_exp_f32_e32 v220, v220
	v_exp_f32_e32 v221, v221
	v_exp_f32_e32 v222, v222
	v_exp_f32_e32 v223, v223
	v_exp_f32_e32 v224, v224
	v_exp_f32_e32 v225, v225
	v_exp_f32_e32 v226, v226
	v_exp_f32_e32 v227, v227
	v_exp_f32_e32 v228, v228
	v_exp_f32_e32 v229, v229
	v_exp_f32_e32 v230, v230
	v_exp_f32_e32 v231, v231
	v_exp_f32_e32 v232, v232
	v_exp_f32_e32 v233, v233
	v_pk_add_f32 v[218:219], v[218:219], v[128:129]
	v_pk_add_f32 v[220:221], v[220:221], v[128:129]
	v_pk_add_f32 v[222:223], v[222:223], v[128:129]
	v_pk_add_f32 v[224:225], v[224:225], v[128:129]
	v_pk_add_f32 v[226:227], v[226:227], v[128:129]
	v_pk_add_f32 v[228:229], v[228:229], v[128:129]
	v_pk_add_f32 v[230:231], v[230:231], v[128:129]
	v_pk_add_f32 v[232:233], v[232:233], v[128:129]
	v_rcp_f32_e32 v218, v218
	v_rcp_f32_e32 v219, v219
	v_rcp_f32_e32 v220, v220
	v_rcp_f32_e32 v221, v221
	v_rcp_f32_e32 v222, v222
	v_rcp_f32_e32 v223, v223
	v_rcp_f32_e32 v224, v224
	v_rcp_f32_e32 v225, v225
	v_rcp_f32_e32 v226, v226
	v_rcp_f32_e32 v227, v227
	v_rcp_f32_e32 v228, v228
	v_rcp_f32_e32 v229, v229
	v_rcp_f32_e32 v230, v230
	v_rcp_f32_e32 v231, v231
	v_rcp_f32_e32 v232, v232
	v_rcp_f32_e32 v233, v233
	v_pk_mul_f32 v[44:45], v[44:45], v[218:219]
	v_pk_mul_f32 v[46:47], v[46:47], v[220:221]
	v_pk_mul_f32 v[40:41], v[40:41], v[222:223]
	v_pk_mul_f32 v[42:43], v[42:43], v[224:225]
	v_pk_mul_f32 v[36:37], v[36:37], v[226:227]
	v_pk_mul_f32 v[38:39], v[38:39], v[228:229]
	v_pk_mul_f32 v[32:33], v[32:33], v[230:231]
	v_pk_mul_f32 v[34:35], v[34:35], v[232:233]
	v_cvt_pk_bf16_f32 v44, v44, v45
	v_cvt_pk_bf16_f32 v45, v46, v47
	v_cvt_pk_bf16_f32 v46, v40, v41
	v_cvt_pk_bf16_f32 v47, v42, v43
	v_cvt_pk_bf16_f32 v36, v36, v37
	v_cvt_pk_bf16_f32 v37, v38, v39
	v_cvt_pk_bf16_f32 v38, v32, v33
	v_cvt_pk_bf16_f32 v39, v34, v35
	v_add_u32_e32 v140, 0xc6000, v139
	global_store_dwordx4 v140, v[44:47], s[8:9]
	v_add_u32_e32 v141, 0xc6100, v139
	global_store_dwordx4 v141, v[36:39], s[8:9]
	v_pk_mul_f32 v[28:29], v[28:29], v[214:215] op_sel_hi:[1,0]
	v_pk_mul_f32 v[30:31], v[30:31], v[214:215] op_sel_hi:[1,0]
	v_pk_mul_f32 v[24:25], v[24:25], v[214:215] op_sel_hi:[1,0]
	v_pk_mul_f32 v[26:27], v[26:27], v[214:215] op_sel_hi:[1,0]
	v_pk_mul_f32 v[20:21], v[20:21], v[214:215] op_sel_hi:[1,0]
	v_pk_mul_f32 v[22:23], v[22:23], v[214:215] op_sel_hi:[1,0]
	v_pk_mul_f32 v[16:17], v[16:17], v[214:215] op_sel_hi:[1,0]
	v_pk_mul_f32 v[18:19], v[18:19], v[214:215] op_sel_hi:[1,0]
	v_pk_mul_f32 v[218:219], v[28:29], v[134:135] op_sel_hi:[1,0]
	v_pk_mul_f32 v[220:221], v[30:31], v[134:135] op_sel_hi:[1,0]
	v_pk_mul_f32 v[222:223], v[24:25], v[134:135] op_sel_hi:[1,0]
	v_pk_mul_f32 v[224:225], v[26:27], v[134:135] op_sel_hi:[1,0]
	v_pk_mul_f32 v[226:227], v[20:21], v[134:135] op_sel_hi:[1,0]
	v_pk_mul_f32 v[228:229], v[22:23], v[134:135] op_sel_hi:[1,0]
	v_pk_mul_f32 v[230:231], v[16:17], v[134:135] op_sel_hi:[1,0]
	v_pk_mul_f32 v[232:233], v[18:19], v[134:135] op_sel_hi:[1,0]
	v_pk_mul_f32 v[218:219], v[28:29], v[218:219]
	v_pk_mul_f32 v[220:221], v[30:31], v[220:221]
	v_pk_mul_f32 v[222:223], v[24:25], v[222:223]
	v_pk_mul_f32 v[224:225], v[26:27], v[224:225]
	v_pk_mul_f32 v[226:227], v[20:21], v[226:227]
	v_pk_mul_f32 v[228:229], v[22:23], v[228:229]
	v_pk_mul_f32 v[230:231], v[16:17], v[230:231]
	v_pk_mul_f32 v[232:233], v[18:19], v[232:233]
	v_pk_fma_f32 v[218:219], v[28:29], v[218:219], v[28:29]
	v_pk_fma_f32 v[220:221], v[30:31], v[220:221], v[30:31]
	v_pk_fma_f32 v[222:223], v[24:25], v[222:223], v[24:25]
	v_pk_fma_f32 v[224:225], v[26:27], v[224:225], v[26:27]
	v_pk_fma_f32 v[226:227], v[20:21], v[226:227], v[20:21]
	v_pk_fma_f32 v[228:229], v[22:23], v[228:229], v[22:23]
	v_pk_fma_f32 v[230:231], v[16:17], v[230:231], v[16:17]
	v_pk_fma_f32 v[232:233], v[18:19], v[232:233], v[18:19]
	v_pk_mul_f32 v[218:219], v[218:219], v[136:137] op_sel_hi:[1,0]
	v_pk_mul_f32 v[220:221], v[220:221], v[136:137] op_sel_hi:[1,0]
	v_pk_mul_f32 v[222:223], v[222:223], v[136:137] op_sel_hi:[1,0]
	v_pk_mul_f32 v[224:225], v[224:225], v[136:137] op_sel_hi:[1,0]
	v_pk_mul_f32 v[226:227], v[226:227], v[136:137] op_sel_hi:[1,0]
	v_pk_mul_f32 v[228:229], v[228:229], v[136:137] op_sel_hi:[1,0]
	v_pk_mul_f32 v[230:231], v[230:231], v[136:137] op_sel_hi:[1,0]
	v_pk_mul_f32 v[232:233], v[232:233], v[136:137] op_sel_hi:[1,0]
	v_pk_mul_f32 v[218:219], v[218:219], v[132:133] op_sel_hi:[1,0]
	v_pk_mul_f32 v[220:221], v[220:221], v[132:133] op_sel_hi:[1,0]
	v_pk_mul_f32 v[222:223], v[222:223], v[132:133] op_sel_hi:[1,0]
	v_pk_mul_f32 v[224:225], v[224:225], v[132:133] op_sel_hi:[1,0]
	v_pk_mul_f32 v[226:227], v[226:227], v[132:133] op_sel_hi:[1,0]
	v_pk_mul_f32 v[228:229], v[228:229], v[132:133] op_sel_hi:[1,0]
	v_pk_mul_f32 v[230:231], v[230:231], v[132:133] op_sel_hi:[1,0]
; __device__ __forceinline__ unsigned pk2(float lo, float hi) { return pg8::cvt_pk_bf16(lo, hi); }
; __device__ __forceinline__ float geluf_(float x) { const float z = 1.5957691216057308f * (x + 0.044715f * x * x * x); return x * sigmoidf_(z); }
; __device__ __forceinline__ float sigmoidf_(float x) { return __builtin_amdgcn_rcpf(1.0f + __expf(-x)); }
; __device__ __forceinline__ float siluf_(float x) { return x * sigmoidf_(x); }
;     __device__ __forceinline__ void operator()(const f32x4 (&acc)[2][2][4][2], const pg8::Unit& u, int wr, int wc, int fr, int fq) const {
;     ...
;             const int act = (pn == 7 || pn == 8) ? 1 : (pn == 10 ? 2 : 0);
; #pragma unroll
;             for (int ai = 0; ai < 2; ++ai)
; #pragma unroll
;                 for (int m = 0; m < 4; ++m) {
;                     const int row = row0 + ai * 128 + m * 16; const float r = rs[ai * 4 + m];
; #pragma unroll
;                     for (int bj = 0; bj < 2; ++bj) {
;                         float v[8];
; #pragma unroll
;                         for (int n = 0; n < 2; ++n)
; #pragma unroll
;                             for (int j = 0; j < 4; ++j) { float t = acc[ai][bj][m][n][j] * r; if (act == 1) t = siluf_(t); else if (act == 2) t = geluf_(t); v[n * 4 + j] = t; }
;                         u32x4 w; w.x = pk2(v[0], v[1]); w.y = pk2(v[2], v[3]); w.z = pk2(v[4], v[5]); w.w = pk2(v[6], v[7]);
;                         *(u32x4*)(Z + (size_t)row * IW + pn * 256 + bj * 128 + wc * 32 + 8 * fq) = w;
;                     }
;                 }
	v_pk_mul_f32 v[232:233], v[232:233], v[132:133] op_sel_hi:[1,0]
	v_exp_f32_e32 v218, v218
	v_exp_f32_e32 v219, v219
	v_exp_f32_e32 v220, v220
	v_exp_f32_e32 v221, v221
	v_exp_f32_e32 v222, v222
	v_exp_f32_e32 v223, v223
	v_exp_f32_e32 v224, v224
	v_exp_f32_e32 v225, v225
	v_exp_f32_e32 v226, v226
	v_exp_f32_e32 v227, v227
	v_exp_f32_e32 v228, v228
	v_exp_f32_e32 v229, v229
	v_exp_f32_e32 v230, v230
	v_exp_f32_e32 v231, v231
	v_exp_f32_e32 v232, v232
	v_exp_f32_e32 v233, v233
	v_pk_add_f32 v[218:219], v[218:219], v[128:129]
	v_pk_add_f32 v[220:221], v[220:221], v[128:129]
	v_pk_add_f32 v[222:223], v[222:223], v[128:129]
	v_pk_add_f32 v[224:225], v[224:225], v[128:129]
	v_pk_add_f32 v[226:227], v[226:227], v[128:129]
	v_pk_add_f32 v[228:229], v[228:229], v[128:129]
	v_pk_add_f32 v[230:231], v[230:231], v[128:129]
	v_pk_add_f32 v[232:233], v[232:233], v[128:129]
	v_rcp_f32_e32 v218, v218
	v_rcp_f32_e32 v219, v219
	v_rcp_f32_e32 v220, v220
	v_rcp_f32_e32 v221, v221
	v_rcp_f32_e32 v222, v222
	v_rcp_f32_e32 v223, v223
	v_rcp_f32_e32 v224, v224
	v_rcp_f32_e32 v225, v225
	v_rcp_f32_e32 v226, v226
	v_rcp_f32_e32 v227, v227
	v_rcp_f32_e32 v228, v228
	v_rcp_f32_e32 v229, v229
	v_rcp_f32_e32 v230, v230
	v_rcp_f32_e32 v231, v231
	v_rcp_f32_e32 v232, v232
	v_rcp_f32_e32 v233, v233
	v_pk_mul_f32 v[28:29], v[28:29], v[218:219]
	v_pk_mul_f32 v[30:31], v[30:31], v[220:221]
	v_pk_mul_f32 v[24:25], v[24:25], v[222:223]
	v_pk_mul_f32 v[26:27], v[26:27], v[224:225]
	v_pk_mul_f32 v[20:21], v[20:21], v[226:227]
	v_pk_mul_f32 v[22:23], v[22:23], v[228:229]
	v_pk_mul_f32 v[16:17], v[16:17], v[230:231]
	v_pk_mul_f32 v[18:19], v[18:19], v[232:233]
	v_cvt_pk_bf16_f32 v28, v28, v29
	v_cvt_pk_bf16_f32 v29, v30, v31
	v_cvt_pk_bf16_f32 v30, v24, v25
	v_cvt_pk_bf16_f32 v31, v26, v27
	v_cvt_pk_bf16_f32 v20, v20, v21
	v_cvt_pk_bf16_f32 v21, v22, v23
	v_cvt_pk_bf16_f32 v22, v16, v17
	v_cvt_pk_bf16_f32 v23, v18, v19
	v_add_u32_e32 v140, 0xdc000, v139
	global_store_dwordx4 v140, v[28:31], s[8:9]
	v_add_u32_e32 v141, 0xdc100, v139
	global_store_dwordx4 v141, v[20:23], s[8:9]
	v_pk_mul_f32 v[12:13], v[12:13], v[216:217] op_sel_hi:[1,0]
	v_pk_mul_f32 v[14:15], v[14:15], v[216:217] op_sel_hi:[1,0]
	v_pk_mul_f32 v[8:9], v[8:9], v[216:217] op_sel_hi:[1,0]
	v_pk_mul_f32 v[10:11], v[10:11], v[216:217] op_sel_hi:[1,0]
	v_pk_mul_f32 v[4:5], v[4:5], v[216:217] op_sel_hi:[1,0]
	v_pk_mul_f32 v[6:7], v[6:7], v[216:217] op_sel_hi:[1,0]
	v_pk_mul_f32 v[0:1], v[0:1], v[216:217] op_sel_hi:[1,0]
	v_pk_mul_f32 v[2:3], v[2:3], v[216:217] op_sel_hi:[1,0]
	v_pk_mul_f32 v[218:219], v[12:13], v[134:135] op_sel_hi:[1,0]
	v_pk_mul_f32 v[220:221], v[14:15], v[134:135] op_sel_hi:[1,0]
	v_pk_mul_f32 v[222:223], v[8:9], v[134:135] op_sel_hi:[1,0]
	v_pk_mul_f32 v[224:225], v[10:11], v[134:135] op_sel_hi:[1,0]
	v_pk_mul_f32 v[226:227], v[4:5], v[134:135] op_sel_hi:[1,0]
	v_pk_mul_f32 v[228:229], v[6:7], v[134:135] op_sel_hi:[1,0]
	v_pk_mul_f32 v[230:231], v[0:1], v[134:135] op_sel_hi:[1,0]
	v_pk_mul_f32 v[232:233], v[2:3], v[134:135] op_sel_hi:[1,0]
	v_pk_mul_f32 v[218:219], v[12:13], v[218:219]
	v_pk_mul_f32 v[220:221], v[14:15], v[220:221]
	v_pk_mul_f32 v[222:223], v[8:9], v[222:223]
	v_pk_mul_f32 v[224:225], v[10:11], v[224:225]
	v_pk_mul_f32 v[226:227], v[4:5], v[226:227]
	v_pk_mul_f32 v[228:229], v[6:7], v[228:229]
	v_pk_mul_f32 v[230:231], v[0:1], v[230:231]
	v_pk_mul_f32 v[232:233], v[2:3], v[232:233]
	v_pk_fma_f32 v[218:219], v[12:13], v[218:219], v[12:13]
	v_pk_fma_f32 v[220:221], v[14:15], v[220:221], v[14:15]
	v_pk_fma_f32 v[222:223], v[8:9], v[222:223], v[8:9]
	v_pk_fma_f32 v[224:225], v[10:11], v[224:225], v[10:11]
	v_pk_fma_f32 v[226:227], v[4:5], v[226:227], v[4:5]
	v_pk_fma_f32 v[228:229], v[6:7], v[228:229], v[6:7]
	v_pk_fma_f32 v[230:231], v[0:1], v[230:231], v[0:1]
	v_pk_fma_f32 v[232:233], v[2:3], v[232:233], v[2:3]
	v_pk_mul_f32 v[218:219], v[218:219], v[136:137] op_sel_hi:[1,0]
	v_pk_mul_f32 v[220:221], v[220:221], v[136:137] op_sel_hi:[1,0]
	v_pk_mul_f32 v[222:223], v[222:223], v[136:137] op_sel_hi:[1,0]
	v_pk_mul_f32 v[224:225], v[224:225], v[136:137] op_sel_hi:[1,0]
	v_pk_mul_f32 v[226:227], v[226:227], v[136:137] op_sel_hi:[1,0]
	v_pk_mul_f32 v[228:229], v[228:229], v[136:137] op_sel_hi:[1,0]
	v_pk_mul_f32 v[230:231], v[230:231], v[136:137] op_sel_hi:[1,0]
	v_pk_mul_f32 v[232:233], v[232:233], v[136:137] op_sel_hi:[1,0]
	v_pk_mul_f32 v[218:219], v[218:219], v[132:133] op_sel_hi:[1,0]
	v_pk_mul_f32 v[220:221], v[220:221], v[132:133] op_sel_hi:[1,0]
	v_pk_mul_f32 v[222:223], v[222:223], v[132:133] op_sel_hi:[1,0]
	v_pk_mul_f32 v[224:225], v[224:225], v[132:133] op_sel_hi:[1,0]
	v_pk_mul_f32 v[226:227], v[226:227], v[132:133] op_sel_hi:[1,0]
	v_pk_mul_f32 v[228:229], v[228:229], v[132:133] op_sel_hi:[1,0]
	v_pk_mul_f32 v[230:231], v[230:231], v[132:133] op_sel_hi:[1,0]
	v_pk_mul_f32 v[232:233], v[232:233], v[132:133] op_sel_hi:[1,0]
	v_exp_f32_e32 v218, v218
	v_exp_f32_e32 v219, v219
	v_exp_f32_e32 v220, v220
	v_exp_f32_e32 v221, v221
	v_exp_f32_e32 v222, v222
	v_exp_f32_e32 v223, v223
	v_exp_f32_e32 v224, v224
	v_exp_f32_e32 v225, v225
	v_exp_f32_e32 v226, v226
	v_exp_f32_e32 v227, v227
	v_exp_f32_e32 v228, v228
	v_exp_f32_e32 v229, v229
	v_exp_f32_e32 v230, v230
	v_exp_f32_e32 v231, v231
	v_exp_f32_e32 v232, v232
	v_exp_f32_e32 v233, v233
	v_pk_add_f32 v[218:219], v[218:219], v[128:129]
	v_pk_add_f32 v[220:221], v[220:221], v[128:129]
	v_pk_add_f32 v[222:223], v[222:223], v[128:129]
	v_pk_add_f32 v[224:225], v[224:225], v[128:129]
	v_pk_add_f32 v[226:227], v[226:227], v[128:129]
	v_pk_add_f32 v[228:229], v[228:229], v[128:129]
	v_pk_add_f32 v[230:231], v[230:231], v[128:129]
	v_pk_add_f32 v[232:233], v[232:233], v[128:129]
	v_rcp_f32_e32 v218, v218
	v_rcp_f32_e32 v219, v219
	v_rcp_f32_e32 v220, v220
	v_rcp_f32_e32 v221, v221
	v_rcp_f32_e32 v222, v222
	v_rcp_f32_e32 v223, v223
	v_rcp_f32_e32 v224, v224
	v_rcp_f32_e32 v225, v225
	v_rcp_f32_e32 v226, v226
	v_rcp_f32_e32 v227, v227
	v_rcp_f32_e32 v228, v228
	v_rcp_f32_e32 v229, v229
	v_rcp_f32_e32 v230, v230
	v_rcp_f32_e32 v231, v231
	v_rcp_f32_e32 v232, v232
	v_rcp_f32_e32 v233, v233
	v_pk_mul_f32 v[12:13], v[12:13], v[218:219]
	v_pk_mul_f32 v[14:15], v[14:15], v[220:221]
	v_pk_mul_f32 v[8:9], v[8:9], v[222:223]
	v_pk_mul_f32 v[10:11], v[10:11], v[224:225]
	v_pk_mul_f32 v[4:5], v[4:5], v[226:227]
	v_pk_mul_f32 v[6:7], v[6:7], v[228:229]
	v_pk_mul_f32 v[0:1], v[0:1], v[230:231]
	v_pk_mul_f32 v[2:3], v[2:3], v[232:233]
	v_cvt_pk_bf16_f32 v12, v12, v13
	v_cvt_pk_bf16_f32 v13, v14, v15
	v_cvt_pk_bf16_f32 v14, v8, v9
	v_cvt_pk_bf16_f32 v15, v10, v11
	v_cvt_pk_bf16_f32 v4, v4, v5
	v_cvt_pk_bf16_f32 v5, v6, v7
	v_cvt_pk_bf16_f32 v6, v0, v1
	v_cvt_pk_bf16_f32 v7, v2, v3
	v_add_u32_e32 v140, 0xf2000, v139
	global_store_dwordx4 v140, v[12:15], s[8:9]
	v_add_u32_e32 v141, 0xf2100, v139
	global_store_dwordx4 v141, v[4:7], s[8:9]
	s_branch .LBB0_1021
